# FFN-up epilogue: gelu argument as x*(c1+c2*x*x) (3 VALU instead of 4), on top of MLA skew + in_cd load hoist
# speedup vs baseline: 1.0086x; 1.0002x over previous
; #define PG8_STAGE(bufoff, gbase, voff) do { _Pragma("unroll") for (int _i = 0; _i < 2; ++_i) \
;         __builtin_amdgcn_global_load_lds((const unsigned*)((const char*)(gbase) + (voff)[_i]), (LAS unsigned*)(lds + (bufoff) + ldsw + _i * 8192), 16, 0, 0); } while (0)
; #define PG8_LDA(dst, b, h) do { _Pragma("unroll") for (int m = 0; m < 4; ++m) _Pragma("unroll") for (int k = 0; k < 2; ++k) dst[m][k] = *(const LAS bf16x8*)(lds + PG8_SA(b, h) + aoff + m * 2048 + k * 1024); } while (0)
; #define PG8_LDB(dst, b, h) do { _Pragma("unroll") for (int n = 0; n < 2; ++n) _Pragma("unroll") for (int k = 0; k < 2; ++k) dst[n][k] = *(const LAS bf16x8*)(lds + PG8_SB(b, h) + boff + n * 2048 + k * 1024); } while (0)
; #define PG8_MMA(ai, bj, At, Bt) do { __builtin_amdgcn_s_setprio(1); _Pragma("unroll") for (int m = 0; m < 4; ++m) _Pragma("unroll") for (int n = 0; n < 2; ++n) _Pragma("unroll") for (int k = 0; k < 2; ++k) \
;         acc[ai][bj][m][n] = __builtin_amdgcn_mfma_f32_16x16x32_bf16(Bt[n][k], At[m][k], acc[ai][bj][m][n], 0, 0, 0); __builtin_amdgcn_s_setprio(0); } while (0)
; #define PG8_BAR __builtin_amdgcn_s_barrier()
; template <class Epi, class Sched, bool APERM, bool ABLK = false, bool RELAX = true>
; __device__ __forceinline__ void gemm_phase(LAS unsigned char* lds, const Gemm g, const Sched& S, const Epi& E) {
;     ...
;             PG8_LDB(B0, 0, 0); PG8_LDB(B1, 0, 1); PG8_SCHED; PG8_LDA(At, 0, 0); PG8_STAGE(PG8_SA(1, 1), a1 + hstepA, voffA);
;             PG8_WAIT_V8R; PG8_WAIT_L(0); PG8_BAR; PG8_MMA(0, 0, At, B0); PG8_MMA(0, 1, At, B1); PG8_BAR; PG8_SCHED;
;             PG8_LDA(At, 0, 1); PG8_STAGE(PG8_SB(0, 0), b2, voffB); PG8_STAGE(PG8_SB(0, 1), b2 + hstepB, voffB); PG8_STAGE(PG8_SA(0, 0), a2, voffA);
;             PG8_WAIT_V8R; PG8_FLAG(0u); PG8_WAIT_L(0); PG8_BAR; PG8_MMA(1, 0, At, B0); PG8_MMA(1, 1, At, B1); PG8_BAR; PG8_SCHED;
;             PG8_LDB(B0, 1, 0); PG8_LDB(B1, 1, 1); PG8_SCHED; PG8_LDA(At, 1, 0); PG8_STAGE(PG8_SA(0, 1), a2 + hstepA, voffA);
;             PG8_WAIT_V(8); PG8_WAIT_L(0); PG8_BAR; PG8_MMA(0, 0, At, B0); PG8_MMA(0, 1, At, B1); PG8_BAR; PG8_SCHED;
;             PG8_LDA(At, 1, 1); PG8_STAGE(PG8_SB(1, 0), b3, voffB); PG8_STAGE(PG8_SB(1, 1), b3 + hstepB, voffB); PG8_STAGE(PG8_SA(1, 0), a3, voffA);
;             PG8_WAIT_V(8); PG8_WAIT_L(0); PG8_BAR; PG8_MMA(1, 0, At, B0); PG8_MMA(1, 1, At, B1); PG8_BAR; PG8_SCHED;
.Lre17:
	s_waitcnt lgkmcnt(0)
	s_barrier
	s_setprio 1
	s_waitcnt lgkmcnt(0)
	v_mfma_f32_16x16x32_bf16 v[54:57], v[122:125], v[162:165], v[54:57]
	v_mfma_f32_16x16x32_bf16 v[50:53], v[134:137], v[162:165], v[50:53]
	v_mfma_f32_16x16x32_bf16 v[38:41], v[122:125], v[188:191], v[38:41]
	v_mfma_f32_16x16x32_bf16 v[34:37], v[134:137], v[188:191], v[34:37]
	v_mfma_f32_16x16x32_bf16 v[30:33], v[122:125], v[206:209], v[30:33]
	v_mfma_f32_16x16x32_bf16 v[22:25], v[134:137], v[206:209], v[22:25]
	v_mfma_f32_16x16x32_bf16 v[14:17], v[122:125], v[214:217], v[14:17]
	v_mfma_f32_16x16x32_bf16 v[10:13], v[134:137], v[214:217], v[10:13]
	v_mfma_f32_16x16x32_bf16 v[54:57], v[126:129], v[166:169], v[54:57]
	v_mfma_f32_16x16x32_bf16 v[50:53], v[138:141], v[166:169], v[50:53]
	v_mfma_f32_16x16x32_bf16 v[38:41], v[126:129], v[202:205], v[38:41]
	v_mfma_f32_16x16x32_bf16 v[34:37], v[138:141], v[202:205], v[34:37]
	v_mfma_f32_16x16x32_bf16 v[30:33], v[126:129], v[210:213], v[30:33]
	v_mfma_f32_16x16x32_bf16 v[22:25], v[138:141], v[210:213], v[22:25]
	v_mfma_f32_16x16x32_bf16 v[14:17], v[126:129], v[218:221], v[14:17]
	v_mfma_f32_16x16x32_bf16 v[10:13], v[138:141], v[218:221], v[10:13]
	s_setprio 0
	s_setprio 1
	v_mfma_f32_16x16x32_bf16 v[62:65], v[142:145], v[162:165], v[62:65]
	v_mfma_f32_16x16x32_bf16 v[58:61], v[150:153], v[162:165], v[58:61]
	v_mfma_f32_16x16x32_bf16 v[46:49], v[142:145], v[188:191], v[46:49]
	v_mfma_f32_16x16x32_bf16 v[42:45], v[150:153], v[188:191], v[42:45]
	v_mfma_f32_16x16x32_bf16 v[26:29], v[142:145], v[206:209], v[26:29]
	v_mfma_f32_16x16x32_bf16 v[18:21], v[150:153], v[206:209], v[18:21]
	v_mfma_f32_16x16x32_bf16 v[6:9], v[142:145], v[214:217], v[6:9]
	v_mfma_f32_16x16x32_bf16 v[2:5], v[150:153], v[214:217], v[2:5]
	v_mfma_f32_16x16x32_bf16 v[62:65], v[146:149], v[166:169], v[62:65]
	v_mfma_f32_16x16x32_bf16 v[58:61], v[154:157], v[166:169], v[58:61]
	v_mfma_f32_16x16x32_bf16 v[46:49], v[146:149], v[202:205], v[46:49]
	v_mfma_f32_16x16x32_bf16 v[42:45], v[154:157], v[202:205], v[42:45]
	v_mfma_f32_16x16x32_bf16 v[26:29], v[146:149], v[210:213], v[26:29]
	v_mfma_f32_16x16x32_bf16 v[18:21], v[154:157], v[210:213], v[18:21]
	v_mfma_f32_16x16x32_bf16 v[6:9], v[146:149], v[218:221], v[6:9]
	v_mfma_f32_16x16x32_bf16 v[2:5], v[154:157], v[218:221], v[2:5]
	s_setprio 0
	s_barrier
	s_add_i32 s74, 0, 0x18000
	s_add_i32 s75, 0, 0x1c000
	v_add_u32_e32 v138, s74, v195
	v_add_u32_e32 v154, s75, v195
	ds_read_b128 v[122:125], v138
	ds_read_b128 v[126:129], v138 offset:1024
	ds_read_b128 v[134:137], v138 offset:2048
	ds_read_b128 v[138:141], v138 offset:3072
	ds_read_b128 v[142:145], v154
	ds_read_b128 v[146:149], v154 offset:1024
	ds_read_b128 v[150:153], v154 offset:2048
	ds_read_b128 v[154:157], v154 offset:3072
	s_add_u32 s0, s66, 0x2000
	s_addc_u32 s1, s67, 0
	s_mov_b32 m0, s39
	v_lshl_add_u64 v[228:229], s[0:1], 0, v[176:177]
	ds_read_b128 v[162:165], v198 offset:32768
	ds_read_b128 v[166:169], v198 offset:33792
	ds_read_b128 v[188:191], v198 offset:34816
	ds_read_b128 v[202:205], v198 offset:35840
	ds_read_b128 v[206:209], v198 offset:36864
	ds_read_b128 v[210:213], v198 offset:37888
	ds_read_b128 v[214:217], v198 offset:38912
	ds_read_b128 v[218:221], v198 offset:39936
	global_load_lds_dwordx4 v[228:229], off
	v_lshl_add_u64 v[228:229], s[0:1], 0, v[172:173]
	s_mov_b32 m0, s40
	s_nop 0
	global_load_lds_dwordx4 v[228:229], off
	s_waitcnt vmcnt(8)
	s_waitcnt lgkmcnt(0)
	s_barrier
	s_setprio 1
	s_waitcnt lgkmcnt(0)
	v_mfma_f32_16x16x32_bf16 v[118:121], v[122:125], v[162:165], v[118:121]
	v_mfma_f32_16x16x32_bf16 v[114:117], v[134:137], v[162:165], v[114:117]
	v_mfma_f32_16x16x32_bf16 v[102:105], v[122:125], v[188:191], v[102:105]
	v_mfma_f32_16x16x32_bf16 v[98:101], v[134:137], v[188:191], v[98:101]
	v_mfma_f32_16x16x32_bf16 v[86:89], v[122:125], v[206:209], v[86:89]
	v_mfma_f32_16x16x32_bf16 v[82:85], v[134:137], v[206:209], v[82:85]
	v_mfma_f32_16x16x32_bf16 v[70:73], v[122:125], v[214:217], v[70:73]
	v_mfma_f32_16x16x32_bf16 v[66:69], v[134:137], v[214:217], v[66:69]
	v_mfma_f32_16x16x32_bf16 v[118:121], v[126:129], v[166:169], v[118:121]
	v_mfma_f32_16x16x32_bf16 v[114:117], v[138:141], v[166:169], v[114:117]
	v_mfma_f32_16x16x32_bf16 v[102:105], v[126:129], v[202:205], v[102:105]
	v_mfma_f32_16x16x32_bf16 v[98:101], v[138:141], v[202:205], v[98:101]
	v_mfma_f32_16x16x32_bf16 v[86:89], v[126:129], v[210:213], v[86:89]
	v_mfma_f32_16x16x32_bf16 v[82:85], v[138:141], v[210:213], v[82:85]
	v_mfma_f32_16x16x32_bf16 v[70:73], v[126:129], v[218:221], v[70:73]
	v_mfma_f32_16x16x32_bf16 v[66:69], v[138:141], v[218:221], v[66:69]
	s_setprio 0
	s_setprio 1
	v_mfma_f32_16x16x32_bf16 v[158:161], v[142:145], v[162:165], v[158:161]
	v_mfma_f32_16x16x32_bf16 v[130:133], v[150:153], v[162:165], v[130:133]
	v_mfma_f32_16x16x32_bf16 v[110:113], v[142:145], v[188:191], v[110:113]
	v_mfma_f32_16x16x32_bf16 v[106:109], v[150:153], v[188:191], v[106:109]
	v_mfma_f32_16x16x32_bf16 v[94:97], v[142:145], v[206:209], v[94:97]
	v_mfma_f32_16x16x32_bf16 v[90:93], v[150:153], v[206:209], v[90:93]
	v_mfma_f32_16x16x32_bf16 v[78:81], v[142:145], v[214:217], v[78:81]
	v_mfma_f32_16x16x32_bf16 v[74:77], v[150:153], v[214:217], v[74:77]
	v_mfma_f32_16x16x32_bf16 v[158:161], v[146:149], v[166:169], v[158:161]
	v_mfma_f32_16x16x32_bf16 v[130:133], v[154:157], v[166:169], v[130:133]
	v_mfma_f32_16x16x32_bf16 v[110:113], v[146:149], v[202:205], v[110:113]
	v_mfma_f32_16x16x32_bf16 v[106:109], v[154:157], v[202:205], v[106:109]
	v_mfma_f32_16x16x32_bf16 v[94:97], v[146:149], v[210:213], v[94:97]
	v_mfma_f32_16x16x32_bf16 v[90:93], v[154:157], v[210:213], v[90:93]
	v_mfma_f32_16x16x32_bf16 v[78:81], v[146:149], v[218:221], v[78:81]
	v_mfma_f32_16x16x32_bf16 v[74:77], v[154:157], v[218:221], v[74:77]
	s_setprio 0
	s_barrier
; #define PG8_STAGE(bufoff, gbase, voff) do { _Pragma("unroll") for (int _i = 0; _i < 2; ++_i) \
;         __builtin_amdgcn_global_load_lds((const unsigned*)((const char*)(gbase) + (voff)[_i]), (LAS unsigned*)(lds + (bufoff) + ldsw + _i * 8192), 16, 0, 0); } while (0)
; #define PG8_LDA(dst, b, h) do { _Pragma("unroll") for (int m = 0; m < 4; ++m) _Pragma("unroll") for (int k = 0; k < 2; ++k) dst[m][k] = *(const LAS bf16x8*)(lds + PG8_SA(b, h) + aoff + m * 2048 + k * 1024); } while (0)
; #define PG8_MMA(ai, bj, At, Bt) do { __builtin_amdgcn_s_setprio(1); _Pragma("unroll") for (int m = 0; m < 4; ++m) _Pragma("unroll") for (int n = 0; n < 2; ++n) _Pragma("unroll") for (int k = 0; k < 2; ++k) \
;         acc[ai][bj][m][n] = __builtin_amdgcn_mfma_f32_16x16x32_bf16(Bt[n][k], At[m][k], acc[ai][bj][m][n], 0, 0, 0); __builtin_amdgcn_s_setprio(0); } while (0)
; #define PG8_WAIT_V(n) asm volatile("s_waitcnt vmcnt(" #n ")" ::: "memory")
; #define PG8_WAIT_L(n) asm volatile("s_waitcnt lgkmcnt(" #n ")" ::: "memory")
; #define PG8_BAR __builtin_amdgcn_s_barrier()
; #define PG8_SCHED __builtin_amdgcn_sched_barrier(0)
; template <class Epi, class Sched, bool APERM, bool ABLK = false, bool RELAX = true>
; __device__ __forceinline__ void gemm_phase(LAS unsigned char* lds, const Gemm g, const Sched& S, const Epi& E) {
;     ...
;             PG8_LDA(At, 1, 1); PG8_STAGE(PG8_SB(1, 0), b3, voffB); PG8_STAGE(PG8_SB(1, 1), b3 + hstepB, voffB); PG8_STAGE(PG8_SA(1, 0), a3, voffA);
;             PG8_WAIT_V(8); PG8_WAIT_L(0); PG8_BAR; PG8_MMA(1, 0, At, B0); PG8_MMA(1, 1, At, B1); PG8_BAR; PG8_SCHED;
;         }
;         if (wr == 0) PG8_BAR;
	s_add_i32 s0, s74, s34
	v_lshl_add_u64 v[192:193], v[192:193], 0, s[8:9]
	s_mov_b32 m0, s0
	ds_read_b128 v[162:165], v198 offset:49152
	ds_read_b128 v[166:169], v198 offset:50176
	ds_read_b128 v[188:191], v198 offset:51200
	ds_read_b128 v[202:205], v198 offset:52224
	ds_read_b128 v[206:209], v198 offset:53248
	ds_read_b128 v[210:213], v198 offset:54272
	ds_read_b128 v[214:217], v198 offset:55296
	ds_read_b128 v[218:221], v198 offset:56320
	global_load_lds_dwordx4 v[192:193], off
	s_add_i32 m0, s0, 0x2000
	s_add_u32 s0, s64, 0x40080
	v_lshl_add_u64 v[192:193], v[222:223], 0, s[8:9]
	s_addc_u32 s1, s65, 0
	s_add_i32 s64, s75, s34
	global_load_lds_dwordx4 v[192:193], off
	v_lshl_add_u64 v[192:193], s[0:1], 0, v[174:175]
	s_mov_b32 m0, s64
	s_nop 0
	global_load_lds_dwordx4 v[192:193], off
	v_lshl_add_u64 v[192:193], s[0:1], 0, v[170:171]
	s_add_i32 m0, s64, 0x2000
	s_nop 0
	global_load_lds_dwordx4 v[192:193], off
	v_lshl_add_u64 v[192:193], v[224:225], 0, s[8:9]
	s_mov_b32 m0, s43
	s_nop 0
	global_load_lds_dwordx4 v[192:193], off
	v_lshl_add_u64 v[192:193], v[226:227], 0, s[8:9]
	s_mov_b32 m0, s44
	s_nop 0
	global_load_lds_dwordx4 v[192:193], off
	s_waitcnt vmcnt(8)
	s_waitcnt lgkmcnt(0)
	s_barrier
	s_setprio 1
	s_waitcnt lgkmcnt(0)
	v_mfma_f32_16x16x32_bf16 v[54:57], v[122:125], v[162:165], v[54:57]
	v_mfma_f32_16x16x32_bf16 v[50:53], v[134:137], v[162:165], v[50:53]
	v_mfma_f32_16x16x32_bf16 v[38:41], v[122:125], v[188:191], v[38:41]
	v_mfma_f32_16x16x32_bf16 v[34:37], v[134:137], v[188:191], v[34:37]
	v_mfma_f32_16x16x32_bf16 v[30:33], v[122:125], v[206:209], v[30:33]
	v_mfma_f32_16x16x32_bf16 v[22:25], v[134:137], v[206:209], v[22:25]
	v_mfma_f32_16x16x32_bf16 v[14:17], v[122:125], v[214:217], v[14:17]
	v_mfma_f32_16x16x32_bf16 v[10:13], v[134:137], v[214:217], v[10:13]
	v_mfma_f32_16x16x32_bf16 v[54:57], v[126:129], v[166:169], v[54:57]
	v_mfma_f32_16x16x32_bf16 v[50:53], v[138:141], v[166:169], v[50:53]
	v_mfma_f32_16x16x32_bf16 v[38:41], v[126:129], v[202:205], v[38:41]
	v_mfma_f32_16x16x32_bf16 v[34:37], v[138:141], v[202:205], v[34:37]
	v_mfma_f32_16x16x32_bf16 v[30:33], v[126:129], v[210:213], v[30:33]
	v_mfma_f32_16x16x32_bf16 v[22:25], v[138:141], v[210:213], v[22:25]
	v_mfma_f32_16x16x32_bf16 v[14:17], v[126:129], v[218:221], v[14:17]
	v_mfma_f32_16x16x32_bf16 v[10:13], v[138:141], v[218:221], v[10:13]
	s_setprio 0
	s_setprio 1
	v_mfma_f32_16x16x32_bf16 v[62:65], v[142:145], v[162:165], v[62:65]
	v_mfma_f32_16x16x32_bf16 v[58:61], v[150:153], v[162:165], v[58:61]
	v_mfma_f32_16x16x32_bf16 v[46:49], v[142:145], v[188:191], v[46:49]
	v_mfma_f32_16x16x32_bf16 v[42:45], v[150:153], v[188:191], v[42:45]
	v_mfma_f32_16x16x32_bf16 v[26:29], v[142:145], v[206:209], v[26:29]
	v_mfma_f32_16x16x32_bf16 v[18:21], v[150:153], v[206:209], v[18:21]
	v_mfma_f32_16x16x32_bf16 v[6:9], v[142:145], v[214:217], v[6:9]
	v_mfma_f32_16x16x32_bf16 v[2:5], v[150:153], v[214:217], v[2:5]
	v_mfma_f32_16x16x32_bf16 v[62:65], v[146:149], v[166:169], v[62:65]
	v_mfma_f32_16x16x32_bf16 v[58:61], v[154:157], v[166:169], v[58:61]
	v_mfma_f32_16x16x32_bf16 v[46:49], v[146:149], v[202:205], v[46:49]
	v_mfma_f32_16x16x32_bf16 v[42:45], v[154:157], v[202:205], v[42:45]
	v_mfma_f32_16x16x32_bf16 v[26:29], v[146:149], v[210:213], v[26:29]
	v_mfma_f32_16x16x32_bf16 v[18:21], v[154:157], v[210:213], v[18:21]
	v_mfma_f32_16x16x32_bf16 v[6:9], v[146:149], v[218:221], v[6:9]
	v_mfma_f32_16x16x32_bf16 v[2:5], v[154:157], v[218:221], v[2:5]
	s_setprio 0
	s_barrier
	s_add_u32 s71, s71, 0x100
	s_addc_u32 s72, s72, 0
	s_cmp_gt_u32 s73, 13
	s_mov_b64 s[0:1], s[62:63]
	s_mov_b32 s64, s73
	s_cbranch_scc0 .LBB0_1246
	v_mov_b32_e32 v252, 0xbdd2d3e7
	s_and_b64 vcc, exec, s[10:11]
	s_cbranch_vccz .LBB0_1249
	s_barrier

;     __device__ __forceinline__ void operator()(const f32x4 (&acc)[2][2][4][2], const pg8::Unit& u, int wr, int wc, int fr, int fq, int buf) const {
;     ...
;             bf16_t* HH = (bf16_t*)(ws + R_HH); float* EP = (float*)(ws + WS_EDGE); float* EG = EP + EDGE_ARR / 4; float* EA = EG + EDGE_ARR / 4;
;             const int jc = u.pn * 128 + wc * 32 + 8 * fq;
;             float w0[8], w1[8], w2[8], cbv[8], pvv[8], nxx[8]; const LAS float* cl = scr + buf * 512 + wc * 32 + 8 * fq;
; #pragma unroll
;             for (int c = 0; c < 8; ++c) { w0[c] = cl[c]; w1[c] = cl[128 + c]; w2[c] = cl[256 + c]; cbv[c] = cl[384 + c];
;                 const float pv_ = __shfl_up(acc[1][0][3][c >> 2][c & 3], 1, 16), nx_ = __shfl_down(acc[0][0][0][c >> 2][c & 3], 1, 16);
;                 pvv[c] = fr == 0 ? 0.f : pv_; nxx[c] = fr == 15 ? 0.f : nx_; }
;             const size_t tok0 = (size_t)u.pm * 256 + wr * 128 + 8 * fr; const int blk = 2 * u.pm + wr;
; #pragma unroll
;             for (int ai = 0; ai < 2; ++ai)
; #pragma unroll
;                 for (int m = 0; m < 4; ++m) {
;                     const int idx = 4 * ai + m; float hv[8], av[8], gv[8];
; #pragma unroll
;                     for (int c = 0; c < 8; ++c) { const int n = c >> 2, jj = c & 3;
;                         const float cur = acc[ai][0][m][n][jj];
;                         const float prev = idx == 0 ? pvv[c] : (m > 0 ? acc[ai][0][m - 1][n][jj] : acc[0][0][3][n][jj]);
;                         const float next = idx == 7 ? nxx[c] : (m < 3 ? acc[ai][0][m + 1][n][jj] : acc[1][0][0][n][jj]);
;                         const float cv = cbv[c] + w0[c] * prev + w1[c] * cur + w2[c] * next;
;                         av[c] = cur; gv[c] = acc[ai][1][m][n][jj]; hv[c] = cv; }
;                     const bool edge0 = (idx == 0 && fr == 0), edge1 = (idx == 7 && fr == 15);
;                     if (edge0 || edge1) { const size_t eo = ((size_t)blk * 2 + (edge1 ? 1 : 0)) * FFH + jc;
; #pragma unroll
;                         for (int c = 0; c < 8; ++c) { EP[eo + c] = hv[c]; EG[eo + c] = gv[c]; EA[eo + c] = av[c]; }
;                     } else { f32x4 o0, o1;
; #pragma unroll
;                         for (int c = 0; c < 4; ++c) { o0[c] = gelu_t(hv[c]) * gv[c]; o1[c] = gelu_t(hv[4 + c]) * gv[4 + c]; }
;                         store8(HH + ((size_t)(u.pn * 4 + wc) * TT + tok0 + idx) * 32 + 8 * fq, o0, o1); }
.LBB0_1251:
	s_lshl_b32 s4, s61, 11
	v_mov_b32_e32 v122, v194
	v_mov_b32_e32 v201, v1
	s_and_b32 s4, s4, 0x800
	s_add_i32 s4, s48, s4
	v_lshlrev_b32_e32 v192, 3, v122
	v_lshl_add_u32 v150, v122, 5, s4
	v_add_u32_e32 v122, -1, v199
	v_and_b32_e32 v123, 0x70, v199
	v_cmp_lt_i32_e32 vcc, v122, v123
	s_ashr_i32 s61, s60, 31
	s_lshl_b64 s[4:5], s[60:61], 8
	v_cndmask_b32_e32 v122, v122, v199, vcc
	v_lshlrev_b32_e32 v162, 2, v122
	v_and_b32_e32 v122, 15, v199
	s_add_u32 s4, s4, s45
	v_cmp_ne_u32_e32 vcc, 15, v122
	ds_bpermute_b32 v164, v162, v14
	ds_bpermute_b32 v165, v162, v15
	s_addc_u32 s5, s5, s46
	s_lshl_b32 s53, s68, 2
	v_addc_co_u32_e32 v122, vcc, 0, v199, vcc
	s_or_b32 s53, s53, s41
	v_lshlrev_b32_e32 v163, 2, v122
	ds_read_b128 v[126:129], v150
	ds_read_b128 v[122:125], v150 offset:16
	ds_read_b128 v[138:141], v150 offset:512
	ds_read_b128 v[134:137], v150 offset:528
	ds_read_b128 v[146:149], v150 offset:1024
	ds_read_b128 v[142:145], v150 offset:1040
	ds_read_b128 v[154:157], v150 offset:1536
	ds_read_b128 v[150:153], v150 offset:1552
	s_mul_hi_i32 s55, s53, 0x9000
	s_mul_i32 s53, s53, 0x9000
	ds_bpermute_b32 v168, v162, v16
	ds_bpermute_b32 v169, v162, v17
	s_add_u32 s62, s4, s53
	s_addc_u32 s63, s5, s55
	v_cmp_eq_u32_e64 s[4:5], 0, v201
	ds_bpermute_b32 v204, v163, v118
	ds_bpermute_b32 v206, v163, v119
	ds_bpermute_b32 v208, v163, v120
	ds_bpermute_b32 v209, v163, v121
	ds_bpermute_b32 v190, v162, v10
	ds_bpermute_b32 v202, v163, v114
	ds_bpermute_b32 v191, v162, v11
	ds_bpermute_b32 v203, v163, v115
	ds_bpermute_b32 v210, v162, v12
	ds_bpermute_b32 v205, v163, v116
	ds_bpermute_b32 v211, v162, v13
	ds_bpermute_b32 v207, v163, v117
	s_waitcnt lgkmcnt(0)
	v_cndmask_b32_e64 v163, v165, 0, s[4:5]
	v_cndmask_b32_e64 v162, v164, 0, s[4:5]
	v_pk_fma_f32 v[162:163], v[126:127], v[162:163], v[154:155]
	v_cndmask_b32_e64 v165, v211, 0, s[4:5]
	v_pk_fma_f32 v[162:163], v[118:119], v[138:139], v[162:163]
	v_cndmask_b32_e64 v164, v210, 0, s[4:5]
	v_pk_fma_f32 v[166:167], v[102:103], v[146:147], v[162:163]
	v_cndmask_b32_e64 v163, v169, 0, s[4:5]
	v_cndmask_b32_e64 v162, v168, 0, s[4:5]
	v_pk_fma_f32 v[162:163], v[128:129], v[162:163], v[156:157]
	v_pk_fma_f32 v[164:165], v[124:125], v[164:165], v[152:153]
	v_pk_fma_f32 v[162:163], v[120:121], v[140:141], v[162:163]
	v_ashrrev_i32_e32 v193, 31, v192
	v_pk_fma_f32 v[168:169], v[104:105], v[148:149], v[162:163]
	v_cndmask_b32_e64 v163, v191, 0, s[4:5]
	v_cndmask_b32_e64 v162, v190, 0, s[4:5]
	v_pk_fma_f32 v[162:163], v[122:123], v[162:163], v[150:151]
	v_pk_fma_f32 v[164:165], v[116:117], v[136:137], v[164:165]
	v_pk_fma_f32 v[162:163], v[114:115], v[134:135], v[162:163]
	v_cmp_ne_u32_e32 vcc, 0, v201
	v_lshl_add_u64 v[188:189], v[192:193], 1, s[16:17]
	v_pk_fma_f32 v[162:163], v[98:99], v[142:143], v[162:163]
	v_pk_fma_f32 v[164:165], v[100:101], v[144:145], v[164:165]
	s_and_saveexec_b64 s[4:5], vcc
	s_xor_b64 s[4:5], exec, s[4:5]
	s_cbranch_execz .LBB0_1253
	v_mul_f32_e32 v210, v162, v162
	v_fmaak_f32 v210, v252, v210, 0xc0135761
	v_mul_f32_e32 v210, v162, v210
	v_mul_f32_e32 v193, v166, v166
	v_fmaak_f32 v193, v252, v193, 0xc0135761
	v_exp_f32_e32 v211, v210
	v_mul_f32_e32 v210, v167, v167
	v_mul_f32_e32 v193, v166, v193
	v_fmaak_f32 v210, v252, v210, 0xc0135761
	v_mul_f32_e32 v210, v167, v210
	v_exp_f32_e32 v193, v193
	v_exp_f32_e32 v212, v210
	v_lshlrev_b32_e32 v190, 3, v201
	v_add_f32_e32 v193, 1.0, v193
	v_rcp_f32_e32 v210, v193
	v_add_f32_e32 v193, 1.0, v211
	v_add_f32_e32 v211, 1.0, v212
	v_mul_f32_e32 v212, v163, v163
	v_fmaak_f32 v212, v252, v212, 0xc0135761
	v_mul_f32_e32 v212, v163, v212
	v_exp_f32_e32 v213, v212
	v_rcp_f32_e32 v211, v211
	v_rcp_f32_e32 v212, v193
	v_ashrrev_i32_e32 v191, 31, v190
	v_add_f32_e32 v193, 1.0, v213
	v_rcp_f32_e32 v213, v193
	v_mul_f32_e32 v193, v168, v168
	v_pk_mul_f32 v[166:167], v[166:167], v[210:211]
	v_fmaak_f32 v193, v252, v193, 0xc0135761
	v_mul_f32_e32 v210, v164, v164
	v_mul_f32_e32 v193, v168, v193
	v_fmaak_f32 v210, v252, v210, 0xc0135761
	v_mul_f32_e32 v210, v164, v210
	v_exp_f32_e32 v193, v193
	v_exp_f32_e32 v211, v210
	v_pk_mul_f32 v[162:163], v[162:163], v[212:213]
	v_add_f32_e32 v193, 1.0, v193
	v_rcp_f32_e32 v210, v193
	v_add_f32_e32 v193, 1.0, v211
	v_mul_f32_e32 v211, v169, v169
	v_fmaak_f32 v211, v252, v211, 0xc0135761
	v_mul_f32_e32 v212, v165, v165
	v_mul_f32_e32 v211, v169, v211
	v_fmaak_f32 v212, v252, v212, 0xc0135761
	v_mul_f32_e32 v212, v165, v212
	v_exp_f32_e32 v211, v211
	v_exp_f32_e32 v213, v212
	v_rcp_f32_e32 v212, v193
	v_add_f32_e32 v193, 1.0, v211
	v_rcp_f32_e32 v211, v193
	v_add_f32_e32 v193, 1.0, v213
	v_rcp_f32_e32 v213, v193
	v_pk_mul_f32 v[214:215], v[130:131], v[162:163]
	v_pk_mul_f32 v[162:163], v[168:169], v[210:211]
	v_lshl_add_u64 v[190:191], s[62:63], 0, v[190:191]
	v_pk_mul_f32 v[168:169], v[160:161], v[162:163]
	v_pk_mul_f32 v[162:163], v[164:165], v[212:213]
	v_pk_mul_f32 v[166:167], v[158:159], v[166:167]
	v_pk_mul_f32 v[210:211], v[132:133], v[162:163]
	v_lshlrev_b64 v[190:191], 6, v[190:191]
	v_lshl_add_u64 v[212:213], v[188:189], 0, v[190:191]
	v_cvt_pk_bf16_f32 v162, v166, v167
	v_cvt_pk_bf16_f32 v163, v168, v169
	v_cvt_pk_bf16_f32 v164, v214, v215
	v_cvt_pk_bf16_f32 v165, v210, v211
	global_store_dwordx4 v[212:213], v[162:165], off

; __device__ __forceinline__ void store8(bf16_t* p, const f32x4& a, const f32x4& b) { u32x4 w; w.x = pk2(a[0], a[1]); w.y = pk2(a[2], a[3]); w.z = pk2(b[0], b[1]); w.w = pk2(b[2], b[3]); *(u32x4*)p = w; }
;     __device__ __forceinline__ bool next(int i, pg8::Unit& u) const { if (!so.next(i, u)) return false; u.pm = (u.pm >> 3) * 9 + 1 + (u.pm & 7); return true; }
; __device__ __forceinline__ float gelu_t(float x) { const float u = x + 0.044715f * x * x * x; return x * __builtin_amdgcn_rcpf(1.f + __builtin_amdgcn_exp2f(-2.302208198f * u)); }
;     __device__ __forceinline__ void operator()(const f32x4 (&acc)[2][2][4][2], const pg8::Unit& u, int wr, int wc, int fr, int fq, int buf) const {
;     ...
;             for (int ai = 0; ai < 2; ++ai)
; #pragma unroll
;                 for (int m = 0; m < 4; ++m) {
;                     const int idx = 4 * ai + m; float hv[8], av[8], gv[8];
; #pragma unroll
;                     for (int c = 0; c < 8; ++c) { const int n = c >> 2, jj = c & 3;
;                         const float cur = acc[ai][0][m][n][jj];
;                         const float prev = idx == 0 ? pvv[c] : (m > 0 ? acc[ai][0][m - 1][n][jj] : acc[0][0][3][n][jj]);
;                         const float next = idx == 7 ? nxx[c] : (m < 3 ? acc[ai][0][m + 1][n][jj] : acc[1][0][0][n][jj]);
;                         const float cv = cbv[c] + w0[c] * prev + w1[c] * cur + w2[c] * next;
;                         av[c] = cur; gv[c] = acc[ai][1][m][n][jj]; hv[c] = cv; }
;                     const bool edge0 = (idx == 0 && fr == 0), edge1 = (idx == 7 && fr == 15);
;                     if (edge0 || edge1) { const size_t eo = ((size_t)blk * 2 + (edge1 ? 1 : 0)) * FFH + jc;
; #pragma unroll
;                         for (int c = 0; c < 8; ++c) { EP[eo + c] = hv[c]; EG[eo + c] = gv[c]; EA[eo + c] = av[c]; }
;                     } else { f32x4 o0, o1;
; #pragma unroll
;                         for (int c = 0; c < 4; ++c) { o0[c] = gelu_t(hv[c]) * gv[c]; o1[c] = gelu_t(hv[4 + c]) * gv[4 + c]; }
;                         store8(HH + ((size_t)(u.pn * 4 + wc) * TT + tok0 + idx) * 32 + 8 * fq, o0, o1); }
.LBB0_1255:
	s_or_b64 exec, exec, s[4:5]
	v_pk_fma_f32 v[118:119], v[118:119], v[126:127], v[154:155]
	v_pk_fma_f32 v[114:115], v[114:115], v[122:123], v[150:151]
	v_pk_fma_f32 v[118:119], v[102:103], v[138:139], v[118:119]
	v_pk_fma_f32 v[114:115], v[98:99], v[134:135], v[114:115]
	v_pk_fma_f32 v[160:161], v[86:87], v[146:147], v[118:119]
	v_pk_fma_f32 v[114:115], v[82:83], v[142:143], v[114:115]
	v_mul_f32_e32 v118, v160, v160
	v_fmaak_f32 v118, v252, v118, 0xc0135761
	v_mul_f32_e32 v119, v161, v161
	v_mul_f32_e32 v118, v160, v118
	v_fmaak_f32 v119, v252, v119, 0xc0135761
	v_mul_f32_e32 v119, v161, v119
	v_exp_f32_e32 v118, v118
	v_exp_f32_e32 v158, v119
	v_pk_fma_f32 v[120:121], v[120:121], v[128:129], v[156:157]
	v_add_f32_e32 v118, 1.0, v118
	v_rcp_f32_e32 v162, v118
	v_add_f32_e32 v118, 1.0, v158
	v_rcp_f32_e32 v163, v118
	v_pk_fma_f32 v[120:121], v[104:105], v[140:141], v[120:121]
	v_pk_fma_f32 v[116:117], v[116:117], v[124:125], v[152:153]
	v_pk_fma_f32 v[120:121], v[88:89], v[148:149], v[120:121]
	v_pk_mul_f32 v[160:161], v[160:161], v[162:163]
	v_mul_f32_e32 v162, v114, v114
	v_mul_f32_e32 v163, v115, v115
	v_fmaak_f32 v162, v252, v162, 0xc0135761
	v_fmaak_f32 v163, v252, v163, 0xc0135761
	v_mul_f32_e32 v162, v114, v162
	v_mul_f32_e32 v163, v115, v163
	v_exp_f32_e32 v162, v162
	v_exp_f32_e32 v163, v163
	v_pk_mul_f32 v[110:111], v[110:111], v[160:161]
	v_pk_fma_f32 v[116:117], v[100:101], v[136:137], v[116:117]
	v_add_f32_e32 v160, 1.0, v162
	v_add_f32_e32 v161, 1.0, v163
	v_mul_f32_e32 v162, v120, v120
	v_mul_f32_e32 v163, v121, v121
	v_fmaak_f32 v162, v252, v162, 0xc0135761
	v_fmaak_f32 v163, v252, v163, 0xc0135761
	v_mul_f32_e32 v162, v120, v162
	v_mul_f32_e32 v163, v121, v163
	v_rcp_f32_e32 v160, v160
	v_rcp_f32_e32 v161, v161
	v_exp_f32_e32 v162, v162
	v_exp_f32_e32 v163, v163
	v_pk_fma_f32 v[116:117], v[84:85], v[144:145], v[116:117]
	v_pk_mul_f32 v[114:115], v[114:115], v[160:161]
	v_add_f32_e32 v160, 1.0, v162
	v_add_f32_e32 v161, 1.0, v163
	v_mul_f32_e32 v162, v116, v116
	v_mul_f32_e32 v163, v117, v117
	v_fmaak_f32 v162, v252, v162, 0xc0135761
	v_fmaak_f32 v163, v252, v163, 0xc0135761
	v_mul_f32_e32 v162, v116, v162
	v_mul_f32_e32 v163, v117, v163
	v_exp_f32_e32 v162, v162
	v_exp_f32_e32 v163, v163
	v_rcp_f32_e32 v160, v160
	v_rcp_f32_e32 v161, v161
	v_add_f32_e32 v162, 1.0, v162
	v_add_f32_e32 v163, 1.0, v163
	v_rcp_f32_e32 v162, v162
	v_rcp_f32_e32 v163, v163
	v_pk_mul_f32 v[114:115], v[106:107], v[114:115]
	v_pk_mul_f32 v[106:107], v[120:121], v[160:161]
	v_pk_fma_f32 v[102:103], v[102:103], v[126:127], v[154:155]
	v_pk_mul_f32 v[112:113], v[112:113], v[106:107]
	v_pk_mul_f32 v[106:107], v[116:117], v[162:163]
	v_pk_fma_f32 v[102:103], v[86:87], v[138:139], v[102:103]
	v_pk_mul_f32 v[116:117], v[108:109], v[106:107]
	v_or_b32_e32 v106, 64, v190
	v_mov_b32_e32 v107, v191
	v_pk_fma_f32 v[102:103], v[70:71], v[146:147], v[102:103]
	v_lshl_add_u64 v[120:121], v[188:189], 0, v[106:107]
	v_mul_f32_e32 v107, v102, v102
	v_fmaak_f32 v107, v252, v107, 0xc0135761
	v_mul_f32_e32 v107, v102, v107
	v_exp_f32_e32 v108, v107
	v_mul_f32_e32 v107, v103, v103
	v_fmaak_f32 v107, v252, v107, 0xc0135761
	v_mul_f32_e32 v107, v103, v107
	v_exp_f32_e32 v109, v107
	v_add_f32_e32 v108, 1.0, v108
	v_pk_fma_f32 v[98:99], v[98:99], v[122:123], v[150:151]
	v_cvt_pk_bf16_f32 v106, v110, v111
	v_rcp_f32_e32 v110, v108
	v_add_f32_e32 v108, 1.0, v109
	v_pk_fma_f32 v[98:99], v[82:83], v[134:135], v[98:99]
	v_cvt_pk_bf16_f32 v107, v112, v113
	v_rcp_f32_e32 v111, v108
	v_cvt_pk_bf16_f32 v108, v114, v115
	v_cvt_pk_bf16_f32 v109, v116, v117
	v_pk_fma_f32 v[98:99], v[66:67], v[142:143], v[98:99]
	global_store_dwordx4 v[120:121], v[106:109], off
	v_pk_fma_f32 v[104:105], v[104:105], v[128:129], v[156:157]
	v_pk_mul_f32 v[102:103], v[102:103], v[110:111]
	v_mul_f32_e32 v106, v98, v98
	v_mul_f32_e32 v107, v99, v99
	v_fmaak_f32 v106, v252, v106, 0xc0135761
	v_fmaak_f32 v107, v252, v107, 0xc0135761
	v_mul_f32_e32 v106, v98, v106
	v_mul_f32_e32 v107, v99, v107
	v_exp_f32_e32 v106, v106
	v_exp_f32_e32 v107, v107
	v_pk_fma_f32 v[104:105], v[88:89], v[140:141], v[104:105]
	v_pk_mul_f32 v[94:95], v[94:95], v[102:103]
	v_pk_fma_f32 v[104:105], v[72:73], v[148:149], v[104:105]
	v_add_f32_e32 v102, 1.0, v106
	v_add_f32_e32 v103, 1.0, v107
	v_mul_f32_e32 v106, v104, v104
	v_mul_f32_e32 v107, v105, v105
	v_fmaak_f32 v106, v252, v106, 0xc0135761
	v_fmaak_f32 v107, v252, v107, 0xc0135761
	v_mul_f32_e32 v106, v104, v106
	v_mul_f32_e32 v107, v105, v107
	v_rcp_f32_e32 v102, v102
	v_rcp_f32_e32 v103, v103
	v_exp_f32_e32 v106, v106
	v_exp_f32_e32 v107, v107
	v_pk_fma_f32 v[100:101], v[100:101], v[124:125], v[152:153]
	v_pk_mul_f32 v[98:99], v[98:99], v[102:103]
	v_pk_fma_f32 v[100:101], v[84:85], v[136:137], v[100:101]
	v_add_f32_e32 v102, 1.0, v106
	v_pk_fma_f32 v[100:101], v[68:69], v[144:145], v[100:101]
	v_add_f32_e32 v103, 1.0, v107
	v_mul_f32_e32 v106, v100, v100
	v_mul_f32_e32 v107, v101, v101
	v_fmaak_f32 v106, v252, v106, 0xc0135761
	v_fmaak_f32 v107, v252, v107, 0xc0135761
	v_mul_f32_e32 v106, v100, v106
	v_mul_f32_e32 v107, v101, v107
	v_exp_f32_e32 v106, v106
	v_exp_f32_e32 v107, v107
	v_rcp_f32_e32 v102, v102
	v_rcp_f32_e32 v103, v103
	v_add_f32_e32 v106, 1.0, v106
	v_add_f32_e32 v107, 1.0, v107
	v_rcp_f32_e32 v106, v106
	v_rcp_f32_e32 v107, v107
	v_pk_mul_f32 v[98:99], v[90:91], v[98:99]
	v_pk_mul_f32 v[90:91], v[104:105], v[102:103]
	v_pk_fma_f32 v[86:87], v[86:87], v[126:127], v[154:155]
	v_pk_mul_f32 v[96:97], v[96:97], v[90:91]
	v_pk_mul_f32 v[90:91], v[100:101], v[106:107]
	v_pk_fma_f32 v[86:87], v[70:71], v[138:139], v[86:87]
	v_pk_mul_f32 v[100:101], v[92:93], v[90:91]
; __device__ __forceinline__ void store8(bf16_t* p, const f32x4& a, const f32x4& b) { u32x4 w; w.x = pk2(a[0], a[1]); w.y = pk2(a[2], a[3]); w.z = pk2(b[0], b[1]); w.w = pk2(b[2], b[3]); *(u32x4*)p = w; }
;     __device__ __forceinline__ bool next(int i, pg8::Unit& u) const { if (!so.next(i, u)) return false; u.pm = (u.pm >> 3) * 9 + 1 + (u.pm & 7); return true; }
; __device__ __forceinline__ float gelu_t(float x) { const float u = x + 0.044715f * x * x * x; return x * __builtin_amdgcn_rcpf(1.f + __builtin_amdgcn_exp2f(-2.302208198f * u)); }
;     __device__ __forceinline__ void operator()(const f32x4 (&acc)[2][2][4][2], const pg8::Unit& u, int wr, int wc, int fr, int fq, int buf) const {
;     ...
;             for (int ai = 0; ai < 2; ++ai)
; #pragma unroll
;                 for (int m = 0; m < 4; ++m) {
;                     const int idx = 4 * ai + m; float hv[8], av[8], gv[8];
; #pragma unroll
;                     for (int c = 0; c < 8; ++c) { const int n = c >> 2, jj = c & 3;
;                         const float cur = acc[ai][0][m][n][jj];
;                         const float prev = idx == 0 ? pvv[c] : (m > 0 ? acc[ai][0][m - 1][n][jj] : acc[0][0][3][n][jj]);
;                         const float next = idx == 7 ? nxx[c] : (m < 3 ? acc[ai][0][m + 1][n][jj] : acc[1][0][0][n][jj]);
;                         const float cv = cbv[c] + w0[c] * prev + w1[c] * cur + w2[c] * next;
;                         av[c] = cur; gv[c] = acc[ai][1][m][n][jj]; hv[c] = cv; }
;                     const bool edge0 = (idx == 0 && fr == 0), edge1 = (idx == 7 && fr == 15);
;                     if (edge0 || edge1) { const size_t eo = ((size_t)blk * 2 + (edge1 ? 1 : 0)) * FFH + jc;
; #pragma unroll
;                         for (int c = 0; c < 8; ++c) { EP[eo + c] = hv[c]; EG[eo + c] = gv[c]; EA[eo + c] = av[c]; }
;                     } else { f32x4 o0, o1;
; #pragma unroll
;                         for (int c = 0; c < 4; ++c) { o0[c] = gelu_t(hv[c]) * gv[c]; o1[c] = gelu_t(hv[4 + c]) * gv[4 + c]; }
;                         store8(HH + ((size_t)(u.pn * 4 + wc) * TT + tok0 + idx) * 32 + 8 * fq, o0, o1); }
	v_or_b32_e32 v90, 0x80, v190
	v_mov_b32_e32 v91, v191
	v_pk_fma_f32 v[86:87], v[54:55], v[146:147], v[86:87]
	v_lshl_add_u64 v[102:103], v[188:189], 0, v[90:91]
	v_mul_f32_e32 v91, v86, v86
	v_fmaak_f32 v91, v252, v91, 0xc0135761
	v_mul_f32_e32 v91, v86, v91
	v_exp_f32_e32 v92, v91
	v_mul_f32_e32 v91, v87, v87
	v_fmaak_f32 v91, v252, v91, 0xc0135761
	v_mul_f32_e32 v91, v87, v91
	v_exp_f32_e32 v93, v91
	v_add_f32_e32 v92, 1.0, v92
	v_pk_fma_f32 v[82:83], v[82:83], v[122:123], v[150:151]
	v_cvt_pk_bf16_f32 v90, v94, v95
	v_rcp_f32_e32 v94, v92
	v_add_f32_e32 v92, 1.0, v93
	v_pk_fma_f32 v[82:83], v[66:67], v[134:135], v[82:83]
	v_cvt_pk_bf16_f32 v91, v96, v97
	v_rcp_f32_e32 v95, v92
	v_cvt_pk_bf16_f32 v92, v98, v99
	v_cvt_pk_bf16_f32 v93, v100, v101
	v_pk_fma_f32 v[82:83], v[50:51], v[142:143], v[82:83]
	global_store_dwordx4 v[102:103], v[90:93], off
	v_pk_fma_f32 v[88:89], v[88:89], v[128:129], v[156:157]
	v_pk_mul_f32 v[86:87], v[86:87], v[94:95]
	v_mul_f32_e32 v90, v82, v82
	v_mul_f32_e32 v91, v83, v83
	v_fmaak_f32 v90, v252, v90, 0xc0135761
	v_fmaak_f32 v91, v252, v91, 0xc0135761
	v_mul_f32_e32 v90, v82, v90
	v_mul_f32_e32 v91, v83, v91
	v_exp_f32_e32 v90, v90
	v_exp_f32_e32 v91, v91
	v_pk_fma_f32 v[88:89], v[72:73], v[140:141], v[88:89]
	v_pk_mul_f32 v[78:79], v[78:79], v[86:87]
	v_pk_fma_f32 v[88:89], v[56:57], v[148:149], v[88:89]
	v_add_f32_e32 v86, 1.0, v90
	v_add_f32_e32 v87, 1.0, v91
	v_mul_f32_e32 v90, v88, v88
	v_mul_f32_e32 v91, v89, v89
	v_fmaak_f32 v90, v252, v90, 0xc0135761
	v_fmaak_f32 v91, v252, v91, 0xc0135761
	v_mul_f32_e32 v90, v88, v90
	v_mul_f32_e32 v91, v89, v91
	v_rcp_f32_e32 v86, v86
	v_rcp_f32_e32 v87, v87
	v_exp_f32_e32 v90, v90
	v_exp_f32_e32 v91, v91
	v_pk_fma_f32 v[84:85], v[84:85], v[124:125], v[152:153]
	v_pk_mul_f32 v[82:83], v[82:83], v[86:87]
	v_pk_fma_f32 v[84:85], v[68:69], v[136:137], v[84:85]
	v_add_f32_e32 v86, 1.0, v90
	v_pk_fma_f32 v[84:85], v[52:53], v[144:145], v[84:85]
	v_add_f32_e32 v87, 1.0, v91
	v_mul_f32_e32 v90, v84, v84
	v_mul_f32_e32 v91, v85, v85
	v_fmaak_f32 v90, v252, v90, 0xc0135761
	v_fmaak_f32 v91, v252, v91, 0xc0135761
	v_mul_f32_e32 v90, v84, v90
	v_mul_f32_e32 v91, v85, v91
	v_exp_f32_e32 v90, v90
	v_exp_f32_e32 v91, v91
	v_rcp_f32_e32 v86, v86
	v_rcp_f32_e32 v87, v87
	v_add_f32_e32 v90, 1.0, v90
	v_add_f32_e32 v91, 1.0, v91
	v_rcp_f32_e32 v90, v90
	v_rcp_f32_e32 v91, v91
	v_pk_mul_f32 v[82:83], v[74:75], v[82:83]
	v_pk_mul_f32 v[74:75], v[88:89], v[86:87]
	v_pk_fma_f32 v[70:71], v[70:71], v[126:127], v[154:155]
	v_pk_mul_f32 v[80:81], v[80:81], v[74:75]
	v_pk_mul_f32 v[74:75], v[84:85], v[90:91]
	v_pk_fma_f32 v[70:71], v[54:55], v[138:139], v[70:71]
	v_pk_mul_f32 v[84:85], v[76:77], v[74:75]
	v_or_b32_e32 v74, 0xc0, v190
	v_mov_b32_e32 v75, v191
	v_pk_fma_f32 v[70:71], v[38:39], v[146:147], v[70:71]
	v_lshl_add_u64 v[86:87], v[188:189], 0, v[74:75]
	v_mul_f32_e32 v75, v70, v70
	v_fmaak_f32 v75, v252, v75, 0xc0135761
	v_mul_f32_e32 v75, v70, v75
	v_exp_f32_e32 v76, v75
	v_mul_f32_e32 v75, v71, v71
	v_fmaak_f32 v75, v252, v75, 0xc0135761
	v_mul_f32_e32 v75, v71, v75
	v_exp_f32_e32 v77, v75
	v_add_f32_e32 v76, 1.0, v76
	v_pk_fma_f32 v[66:67], v[66:67], v[122:123], v[150:151]
	v_cvt_pk_bf16_f32 v74, v78, v79
	v_rcp_f32_e32 v78, v76
	v_add_f32_e32 v76, 1.0, v77
	v_pk_fma_f32 v[66:67], v[50:51], v[134:135], v[66:67]
	v_cvt_pk_bf16_f32 v75, v80, v81
	v_rcp_f32_e32 v79, v76
	v_cvt_pk_bf16_f32 v76, v82, v83
	v_cvt_pk_bf16_f32 v77, v84, v85
	v_pk_fma_f32 v[66:67], v[34:35], v[142:143], v[66:67]
	global_store_dwordx4 v[86:87], v[74:77], off
	v_pk_fma_f32 v[72:73], v[72:73], v[128:129], v[156:157]
	v_pk_mul_f32 v[70:71], v[70:71], v[78:79]
	v_mul_f32_e32 v74, v66, v66
	v_mul_f32_e32 v75, v67, v67
	v_fmaak_f32 v74, v252, v74, 0xc0135761
	v_fmaak_f32 v75, v252, v75, 0xc0135761
	v_mul_f32_e32 v74, v66, v74
	v_mul_f32_e32 v75, v67, v75
	v_exp_f32_e32 v74, v74
	v_exp_f32_e32 v75, v75
	v_pk_fma_f32 v[72:73], v[56:57], v[140:141], v[72:73]
	v_pk_mul_f32 v[62:63], v[62:63], v[70:71]
	v_pk_fma_f32 v[72:73], v[40:41], v[148:149], v[72:73]
	v_add_f32_e32 v70, 1.0, v74
	v_add_f32_e32 v71, 1.0, v75
	v_mul_f32_e32 v74, v72, v72
	v_mul_f32_e32 v75, v73, v73
	v_fmaak_f32 v74, v252, v74, 0xc0135761
	v_fmaak_f32 v75, v252, v75, 0xc0135761
	v_mul_f32_e32 v74, v72, v74
	v_mul_f32_e32 v75, v73, v75
	v_rcp_f32_e32 v70, v70
	v_rcp_f32_e32 v71, v71
	v_exp_f32_e32 v74, v74
	v_exp_f32_e32 v75, v75
	v_pk_fma_f32 v[68:69], v[68:69], v[124:125], v[152:153]
	v_pk_mul_f32 v[66:67], v[66:67], v[70:71]
	v_pk_fma_f32 v[68:69], v[52:53], v[136:137], v[68:69]
	v_add_f32_e32 v70, 1.0, v74
	v_pk_fma_f32 v[68:69], v[36:37], v[144:145], v[68:69]
	v_add_f32_e32 v71, 1.0, v75
	v_mul_f32_e32 v74, v68, v68
	v_mul_f32_e32 v75, v69, v69
	v_fmaak_f32 v74, v252, v74, 0xc0135761
	v_fmaak_f32 v75, v252, v75, 0xc0135761
	v_mul_f32_e32 v74, v68, v74
	v_mul_f32_e32 v75, v69, v75
	v_exp_f32_e32 v74, v74
	v_exp_f32_e32 v75, v75
	v_rcp_f32_e32 v70, v70
	v_rcp_f32_e32 v71, v71
	v_add_f32_e32 v74, 1.0, v74
	v_add_f32_e32 v75, 1.0, v75
	v_rcp_f32_e32 v74, v74
	v_rcp_f32_e32 v75, v75
	v_pk_mul_f32 v[66:67], v[58:59], v[66:67]
	v_pk_mul_f32 v[58:59], v[72:73], v[70:71]
	v_pk_fma_f32 v[54:55], v[54:55], v[126:127], v[154:155]
	v_pk_mul_f32 v[64:65], v[64:65], v[58:59]
	v_pk_mul_f32 v[58:59], v[68:69], v[74:75]
	v_pk_fma_f32 v[54:55], v[38:39], v[138:139], v[54:55]
	v_pk_mul_f32 v[68:69], v[60:61], v[58:59]
	v_or_b32_e32 v58, 0x100, v190
	v_mov_b32_e32 v59, v191
	v_pk_fma_f32 v[54:55], v[30:31], v[146:147], v[54:55]
	v_lshl_add_u64 v[70:71], v[188:189], 0, v[58:59]
	v_mul_f32_e32 v59, v54, v54
	v_fmaak_f32 v59, v252, v59, 0xc0135761
; __device__ __forceinline__ void store8(bf16_t* p, const f32x4& a, const f32x4& b) { u32x4 w; w.x = pk2(a[0], a[1]); w.y = pk2(a[2], a[3]); w.z = pk2(b[0], b[1]); w.w = pk2(b[2], b[3]); *(u32x4*)p = w; }
;     __device__ __forceinline__ bool next(int i, pg8::Unit& u) const { if (!so.next(i, u)) return false; u.pm = (u.pm >> 3) * 9 + 1 + (u.pm & 7); return true; }
; __device__ __forceinline__ float gelu_t(float x) { const float u = x + 0.044715f * x * x * x; return x * __builtin_amdgcn_rcpf(1.f + __builtin_amdgcn_exp2f(-2.302208198f * u)); }
;     __device__ __forceinline__ void operator()(const f32x4 (&acc)[2][2][4][2], const pg8::Unit& u, int wr, int wc, int fr, int fq, int buf) const {
;     ...
;             for (int ai = 0; ai < 2; ++ai)
; #pragma unroll
;                 for (int m = 0; m < 4; ++m) {
;                     const int idx = 4 * ai + m; float hv[8], av[8], gv[8];
; #pragma unroll
;                     for (int c = 0; c < 8; ++c) { const int n = c >> 2, jj = c & 3;
;                         const float cur = acc[ai][0][m][n][jj];
;                         const float prev = idx == 0 ? pvv[c] : (m > 0 ? acc[ai][0][m - 1][n][jj] : acc[0][0][3][n][jj]);
;                         const float next = idx == 7 ? nxx[c] : (m < 3 ? acc[ai][0][m + 1][n][jj] : acc[1][0][0][n][jj]);
;                         const float cv = cbv[c] + w0[c] * prev + w1[c] * cur + w2[c] * next;
;                         av[c] = cur; gv[c] = acc[ai][1][m][n][jj]; hv[c] = cv; }
;                     const bool edge0 = (idx == 0 && fr == 0), edge1 = (idx == 7 && fr == 15);
;                     if (edge0 || edge1) { const size_t eo = ((size_t)blk * 2 + (edge1 ? 1 : 0)) * FFH + jc;
; #pragma unroll
;                         for (int c = 0; c < 8; ++c) { EP[eo + c] = hv[c]; EG[eo + c] = gv[c]; EA[eo + c] = av[c]; }
;                     } else { f32x4 o0, o1;
; #pragma unroll
;                         for (int c = 0; c < 4; ++c) { o0[c] = gelu_t(hv[c]) * gv[c]; o1[c] = gelu_t(hv[4 + c]) * gv[4 + c]; }
;                         store8(HH + ((size_t)(u.pn * 4 + wc) * TT + tok0 + idx) * 32 + 8 * fq, o0, o1); }
	v_mul_f32_e32 v59, v54, v59
	v_exp_f32_e32 v60, v59
	v_mul_f32_e32 v59, v55, v55
	v_fmaak_f32 v59, v252, v59, 0xc0135761
	v_mul_f32_e32 v59, v55, v59
	v_exp_f32_e32 v61, v59
	v_add_f32_e32 v60, 1.0, v60
	v_pk_fma_f32 v[50:51], v[50:51], v[122:123], v[150:151]
	v_cvt_pk_bf16_f32 v58, v62, v63
	v_rcp_f32_e32 v62, v60
	v_add_f32_e32 v60, 1.0, v61
	v_pk_fma_f32 v[50:51], v[34:35], v[134:135], v[50:51]
	v_cvt_pk_bf16_f32 v59, v64, v65
	v_rcp_f32_e32 v63, v60
	v_cvt_pk_bf16_f32 v60, v66, v67
	v_cvt_pk_bf16_f32 v61, v68, v69
	v_pk_fma_f32 v[50:51], v[22:23], v[142:143], v[50:51]
	global_store_dwordx4 v[70:71], v[58:61], off
	v_pk_fma_f32 v[56:57], v[56:57], v[128:129], v[156:157]
	v_pk_mul_f32 v[54:55], v[54:55], v[62:63]
	v_mul_f32_e32 v58, v50, v50
	v_mul_f32_e32 v59, v51, v51
	v_fmaak_f32 v58, v252, v58, 0xc0135761
	v_fmaak_f32 v59, v252, v59, 0xc0135761
	v_mul_f32_e32 v58, v50, v58
	v_mul_f32_e32 v59, v51, v59
	v_exp_f32_e32 v58, v58
	v_exp_f32_e32 v59, v59
	v_pk_fma_f32 v[56:57], v[40:41], v[140:141], v[56:57]
	v_pk_mul_f32 v[46:47], v[46:47], v[54:55]
	v_pk_fma_f32 v[56:57], v[32:33], v[148:149], v[56:57]
	v_add_f32_e32 v54, 1.0, v58
	v_add_f32_e32 v55, 1.0, v59
	v_mul_f32_e32 v58, v56, v56
	v_mul_f32_e32 v59, v57, v57
	v_fmaak_f32 v58, v252, v58, 0xc0135761
	v_fmaak_f32 v59, v252, v59, 0xc0135761
	v_mul_f32_e32 v58, v56, v58
	v_mul_f32_e32 v59, v57, v59
	v_rcp_f32_e32 v54, v54
	v_rcp_f32_e32 v55, v55
	v_exp_f32_e32 v58, v58
	v_exp_f32_e32 v59, v59
	v_pk_fma_f32 v[52:53], v[52:53], v[124:125], v[152:153]
	v_pk_mul_f32 v[50:51], v[50:51], v[54:55]
	v_pk_fma_f32 v[52:53], v[36:37], v[136:137], v[52:53]
	v_add_f32_e32 v54, 1.0, v58
	v_pk_fma_f32 v[52:53], v[24:25], v[144:145], v[52:53]
	v_add_f32_e32 v55, 1.0, v59
	v_mul_f32_e32 v58, v52, v52
	v_mul_f32_e32 v59, v53, v53
	v_fmaak_f32 v58, v252, v58, 0xc0135761
	v_fmaak_f32 v59, v252, v59, 0xc0135761
	v_mul_f32_e32 v58, v52, v58
	v_mul_f32_e32 v59, v53, v59
	v_exp_f32_e32 v58, v58
	v_exp_f32_e32 v59, v59
	v_rcp_f32_e32 v54, v54
	v_rcp_f32_e32 v55, v55
	v_add_f32_e32 v58, 1.0, v58
	v_add_f32_e32 v59, 1.0, v59
	v_rcp_f32_e32 v58, v58
	v_rcp_f32_e32 v59, v59
	v_pk_mul_f32 v[50:51], v[42:43], v[50:51]
	v_pk_mul_f32 v[42:43], v[56:57], v[54:55]
	v_pk_fma_f32 v[38:39], v[38:39], v[126:127], v[154:155]
	v_pk_mul_f32 v[48:49], v[48:49], v[42:43]
	v_pk_mul_f32 v[42:43], v[52:53], v[58:59]
	v_pk_fma_f32 v[38:39], v[30:31], v[138:139], v[38:39]
	v_pk_mul_f32 v[52:53], v[44:45], v[42:43]
	v_or_b32_e32 v42, 0x140, v190
	v_mov_b32_e32 v43, v191
	v_pk_fma_f32 v[38:39], v[14:15], v[146:147], v[38:39]
	v_lshl_add_u64 v[54:55], v[188:189], 0, v[42:43]
	v_mul_f32_e32 v43, v38, v38
	v_fmaak_f32 v43, v252, v43, 0xc0135761
	v_mul_f32_e32 v43, v38, v43
	v_exp_f32_e32 v44, v43
	v_mul_f32_e32 v43, v39, v39
	v_fmaak_f32 v43, v252, v43, 0xc0135761
	v_mul_f32_e32 v43, v39, v43
	v_exp_f32_e32 v45, v43
	v_add_f32_e32 v44, 1.0, v44
	v_pk_fma_f32 v[34:35], v[34:35], v[122:123], v[150:151]
	v_cvt_pk_bf16_f32 v42, v46, v47
	v_rcp_f32_e32 v46, v44
	v_add_f32_e32 v44, 1.0, v45
	v_pk_fma_f32 v[34:35], v[22:23], v[134:135], v[34:35]
	v_cvt_pk_bf16_f32 v43, v48, v49
	v_rcp_f32_e32 v47, v44
	v_cvt_pk_bf16_f32 v44, v50, v51
	v_cvt_pk_bf16_f32 v45, v52, v53
	v_pk_fma_f32 v[34:35], v[10:11], v[142:143], v[34:35]
	global_store_dwordx4 v[54:55], v[42:45], off
	v_pk_fma_f32 v[40:41], v[40:41], v[128:129], v[156:157]
	v_pk_mul_f32 v[38:39], v[38:39], v[46:47]
	v_mul_f32_e32 v42, v34, v34
	v_mul_f32_e32 v43, v35, v35
	v_fmaak_f32 v42, v252, v42, 0xc0135761
	v_fmaak_f32 v43, v252, v43, 0xc0135761
	v_mul_f32_e32 v42, v34, v42
	v_mul_f32_e32 v43, v35, v43
	v_exp_f32_e32 v42, v42
	v_exp_f32_e32 v43, v43
	v_pk_fma_f32 v[40:41], v[32:33], v[140:141], v[40:41]
	v_pk_mul_f32 v[26:27], v[26:27], v[38:39]
	v_pk_fma_f32 v[40:41], v[16:17], v[148:149], v[40:41]
	v_add_f32_e32 v38, 1.0, v42
	v_add_f32_e32 v39, 1.0, v43
	v_mul_f32_e32 v42, v40, v40
	v_mul_f32_e32 v43, v41, v41
	v_fmaak_f32 v42, v252, v42, 0xc0135761
	v_fmaak_f32 v43, v252, v43, 0xc0135761
	v_mul_f32_e32 v42, v40, v42
	v_mul_f32_e32 v43, v41, v43
	v_rcp_f32_e32 v38, v38
	v_rcp_f32_e32 v39, v39
	v_exp_f32_e32 v42, v42
	v_exp_f32_e32 v43, v43
	v_pk_fma_f32 v[36:37], v[36:37], v[124:125], v[152:153]
	v_pk_mul_f32 v[34:35], v[34:35], v[38:39]
	v_pk_fma_f32 v[36:37], v[24:25], v[136:137], v[36:37]
	v_add_f32_e32 v38, 1.0, v42
	v_pk_fma_f32 v[36:37], v[12:13], v[144:145], v[36:37]
	v_add_f32_e32 v39, 1.0, v43
	v_mul_f32_e32 v42, v36, v36
	v_mul_f32_e32 v43, v37, v37
	v_fmaak_f32 v42, v252, v42, 0xc0135761
	v_fmaak_f32 v43, v252, v43, 0xc0135761
	v_mul_f32_e32 v42, v36, v42
	v_mul_f32_e32 v43, v37, v43
	v_exp_f32_e32 v42, v42
	v_exp_f32_e32 v43, v43
	v_rcp_f32_e32 v38, v38
	v_rcp_f32_e32 v39, v39
	v_add_f32_e32 v42, 1.0, v42
	v_add_f32_e32 v43, 1.0, v43
	v_rcp_f32_e32 v42, v42
	v_rcp_f32_e32 v43, v43
	v_pk_mul_f32 v[34:35], v[18:19], v[34:35]
	v_pk_mul_f32 v[18:19], v[40:41], v[38:39]
	v_cmp_eq_u32_e64 s[4:5], 15, v201
	v_pk_mul_f32 v[28:29], v[28:29], v[18:19]
	v_pk_mul_f32 v[18:19], v[36:37], v[42:43]
	v_cndmask_b32_e64 v131, v206, 0, s[4:5]
	v_pk_mul_f32 v[36:37], v[20:21], v[18:19]
	v_or_b32_e32 v18, 0x180, v190
	v_mov_b32_e32 v19, v191
	v_lshl_add_u64 v[38:39], v[188:189], 0, v[18:19]
	v_cvt_pk_bf16_f32 v18, v26, v27
	v_cvt_pk_bf16_f32 v19, v28, v29
	v_cvt_pk_bf16_f32 v20, v34, v35
	v_cvt_pk_bf16_f32 v21, v36, v37
	global_store_dwordx4 v[38:39], v[18:21], off
	v_cndmask_b32_e64 v130, v204, 0, s[4:5]
	v_cndmask_b32_e64 v133, v209, 0, s[4:5]
	v_pk_fma_f32 v[18:19], v[30:31], v[126:127], v[154:155]
	v_cndmask_b32_e64 v132, v208, 0, s[4:5]
	v_pk_fma_f32 v[18:19], v[14:15], v[138:139], v[18:19]
	v_pk_fma_f32 v[20:21], v[24:25], v[124:125], v[152:153]
	v_pk_fma_f32 v[26:27], v[146:147], v[130:131], v[18:19]
	v_pk_fma_f32 v[18:19], v[32:33], v[128:129], v[156:157]
	v_cndmask_b32_e64 v119, v203, 0, s[4:5]
	v_pk_fma_f32 v[18:19], v[16:17], v[140:141], v[18:19]
	v_cndmask_b32_e64 v118, v202, 0, s[4:5]
	v_pk_fma_f32 v[28:29], v[148:149], v[132:133], v[18:19]
	v_pk_fma_f32 v[18:19], v[22:23], v[122:123], v[150:151]
	v_cndmask_b32_e64 v159, v207, 0, s[4:5]
	v_cndmask_b32_e64 v158, v205, 0, s[4:5]
	v_pk_fma_f32 v[18:19], v[10:11], v[134:135], v[18:19]
	v_pk_fma_f32 v[20:21], v[12:13], v[136:137], v[20:21]
	v_cmp_ne_u32_e32 vcc, 15, v201
	v_pk_fma_f32 v[18:19], v[142:143], v[118:119], v[18:19]
	v_pk_fma_f32 v[20:21], v[144:145], v[158:159], v[20:21]
	s_and_saveexec_b64 s[4:5], vcc
	s_xor_b64 s[4:5], exec, s[4:5]
	s_cbranch_execnz .LBB0_1258
	s_andn2_saveexec_b64 s[4:5], s[4:5]
	s_cbranch_execnz .LBB0_1259

; __device__ __forceinline__ void store8(bf16_t* p, const f32x4& a, const f32x4& b) { u32x4 w; w.x = pk2(a[0], a[1]); w.y = pk2(a[2], a[3]); w.z = pk2(b[0], b[1]); w.w = pk2(b[2], b[3]); *(u32x4*)p = w; }
;     __device__ __forceinline__ bool next(int i, pg8::Unit& u) const { if (!so.next(i, u)) return false; u.pm = (u.pm >> 3) * 9 + 1 + (u.pm & 7); return true; }
; __device__ __forceinline__ float gelu_t(float x) { const float u = x + 0.044715f * x * x * x; return x * __builtin_amdgcn_rcpf(1.f + __builtin_amdgcn_exp2f(-2.302208198f * u)); }
;     __device__ __forceinline__ void operator()(const f32x4 (&acc)[2][2][4][2], const pg8::Unit& u, int wr, int wc, int fr, int fq, int buf) const {
;     ...
;             for (int ai = 0; ai < 2; ++ai)
; #pragma unroll
;                 for (int m = 0; m < 4; ++m) {
;                     const int idx = 4 * ai + m; float hv[8], av[8], gv[8];
; #pragma unroll
;                     for (int c = 0; c < 8; ++c) { const int n = c >> 2, jj = c & 3;
;                         const float cur = acc[ai][0][m][n][jj];
;                         const float prev = idx == 0 ? pvv[c] : (m > 0 ? acc[ai][0][m - 1][n][jj] : acc[0][0][3][n][jj]);
;                         const float next = idx == 7 ? nxx[c] : (m < 3 ? acc[ai][0][m + 1][n][jj] : acc[1][0][0][n][jj]);
;                         const float cv = cbv[c] + w0[c] * prev + w1[c] * cur + w2[c] * next;
;                         av[c] = cur; gv[c] = acc[ai][1][m][n][jj]; hv[c] = cv; }
;                     const bool edge0 = (idx == 0 && fr == 0), edge1 = (idx == 7 && fr == 15);
;                     if (edge0 || edge1) { const size_t eo = ((size_t)blk * 2 + (edge1 ? 1 : 0)) * FFH + jc;
; #pragma unroll
;                         for (int c = 0; c < 8; ++c) { EP[eo + c] = hv[c]; EG[eo + c] = gv[c]; EA[eo + c] = av[c]; }
;                     } else { f32x4 o0, o1;
; #pragma unroll
;                         for (int c = 0; c < 4; ++c) { o0[c] = gelu_t(hv[c]) * gv[c]; o1[c] = gelu_t(hv[4 + c]) * gv[4 + c]; }
;                         store8(HH + ((size_t)(u.pn * 4 + wc) * TT + tok0 + idx) * 32 + 8 * fq, o0, o1); }
.LBB0_1258:
	v_mul_f32_e32 v13, v18, v18
	v_mul_f32_e32 v16, v27, v27
	v_fmaak_f32 v13, v252, v13, 0xc0135761
	v_fmaak_f32 v16, v252, v16, 0xc0135761
	v_mul_f32_e32 v13, v18, v13
	v_mul_f32_e32 v16, v27, v16
	v_exp_f32_e32 v13, v13
	v_exp_f32_e32 v16, v16
	v_mul_f32_e32 v23, v20, v20
	v_fmaak_f32 v23, v252, v23, 0xc0135761
	v_add_f32_e32 v17, 1.0, v13
	v_add_f32_e32 v13, 1.0, v16
	v_mul_f32_e32 v16, v19, v19
	v_fmaak_f32 v16, v252, v16, 0xc0135761
	v_mul_f32_e32 v16, v19, v16
	v_exp_f32_e32 v22, v16
	v_rcp_f32_e32 v16, v17
	v_mul_f32_e32 v23, v20, v23
	v_add_f32_e32 v17, 1.0, v22
	v_mul_f32_e32 v22, v28, v28
	v_fmaak_f32 v22, v252, v22, 0xc0135761
	v_mul_f32_e32 v22, v28, v22
	v_rcp_f32_e32 v17, v17
	v_exp_f32_e32 v22, v22
	v_exp_f32_e32 v23, v23
	v_mul_f32_e32 v12, v26, v26
	v_pk_mul_f32 v[16:17], v[18:19], v[16:17]
	v_add_f32_e32 v18, 1.0, v22
	v_mul_f32_e32 v22, v29, v29
	v_fmaak_f32 v22, v252, v22, 0xc0135761
	v_mul_f32_e32 v22, v29, v22
	v_add_f32_e32 v19, 1.0, v23
	v_exp_f32_e32 v23, v22
	v_mul_f32_e32 v22, v21, v21
	v_fmaak_f32 v12, v252, v12, 0xc0135761
	v_fmaak_f32 v22, v252, v22, 0xc0135761
	v_mul_f32_e32 v12, v26, v12
	v_mul_f32_e32 v22, v21, v22
	v_exp_f32_e32 v12, v12
	v_exp_f32_e32 v24, v22
	v_rcp_f32_e32 v22, v19
	v_add_f32_e32 v19, 1.0, v23
	v_add_f32_e32 v12, 1.0, v12
	v_rcp_f32_e32 v18, v18
	v_rcp_f32_e32 v19, v19
	v_add_f32_e32 v23, 1.0, v24
	v_rcp_f32_e32 v12, v12
	v_rcp_f32_e32 v13, v13
	v_rcp_f32_e32 v23, v23
	v_pk_mul_f32 v[24:25], v[2:3], v[16:17]
	v_pk_mul_f32 v[16:17], v[28:29], v[18:19]
	v_pk_mul_f32 v[12:13], v[26:27], v[12:13]
	v_pk_mul_f32 v[18:19], v[8:9], v[16:17]
	v_pk_mul_f32 v[16:17], v[20:21], v[22:23]
	v_pk_mul_f32 v[12:13], v[6:7], v[12:13]
	v_pk_mul_f32 v[20:21], v[4:5], v[16:17]
	v_or_b32_e32 v190, 0x1c0, v190
	v_lshl_add_u64 v[22:23], v[188:189], 0, v[190:191]
	v_cvt_pk_bf16_f32 v16, v12, v13
	v_cvt_pk_bf16_f32 v17, v18, v19
	v_cvt_pk_bf16_f32 v18, v24, v25
	v_cvt_pk_bf16_f32 v19, v20, v21
	global_store_dwordx4 v[22:23], v[16:19], off
	s_andn2_saveexec_b64 s[4:5], s[4:5]
	s_cbranch_execz .LBB0_1257

; #define PG8_STAGE(bufoff, gbase, voff) do { _Pragma("unroll") for (int _i = 0; _i < 2; ++_i) \
;         __builtin_amdgcn_global_load_lds((const unsigned*)((const char*)(gbase) + (voff)[_i]), (LAS unsigned*)(lds + (bufoff) + ldsw + _i * 8192), 16, 0, 0); } while (0)
; #define PG8_LDA(dst, b, h) do { _Pragma("unroll") for (int m = 0; m < 4; ++m) _Pragma("unroll") for (int k = 0; k < 2; ++k) dst[m][k] = *(const LAS bf16x8*)(lds + PG8_SA(b, h) + aoff + m * 2048 + k * 1024); } while (0)
; #define PG8_LDB(dst, b, h) do { _Pragma("unroll") for (int n = 0; n < 2; ++n) _Pragma("unroll") for (int k = 0; k < 2; ++k) dst[n][k] = *(const LAS bf16x8*)(lds + PG8_SB(b, h) + boff + n * 2048 + k * 1024); } while (0)
; #define PG8_MMA(ai, bj, At, Bt) do { __builtin_amdgcn_s_setprio(1); _Pragma("unroll") for (int m = 0; m < 4; ++m) _Pragma("unroll") for (int n = 0; n < 2; ++n) _Pragma("unroll") for (int k = 0; k < 2; ++k) \
;         acc[ai][bj][m][n] = __builtin_amdgcn_mfma_f32_16x16x32_bf16(Bt[n][k], At[m][k], acc[ai][bj][m][n], 0, 0, 0); __builtin_amdgcn_s_setprio(0); } while (0)
; #define PG8_BAR __builtin_amdgcn_s_barrier()
; template <class Epi, class Sched, bool APERM, bool ABLK = false, bool RELAX = true>
; __device__ __forceinline__ void gemm_phase(LAS unsigned char* lds, const Gemm g, const Sched& S, const Epi& E) {
;     ...
;             PG8_LDB(B0, 0, 0); PG8_LDB(B1, 0, 1); PG8_SCHED; PG8_LDA(At, 0, 0); PG8_STAGE(PG8_SA(1, 1), a1 + hstepA, voffA);
;             PG8_WAIT_V8R; PG8_WAIT_L(0); PG8_BAR; PG8_MMA(0, 0, At, B0); PG8_MMA(0, 1, At, B1); PG8_BAR; PG8_SCHED;
;             PG8_LDA(At, 0, 1); PG8_STAGE(PG8_SB(0, 0), b2, voffB); PG8_STAGE(PG8_SB(0, 1), b2 + hstepB, voffB); PG8_STAGE(PG8_SA(0, 0), a2, voffA);
;             PG8_WAIT_V8R; PG8_FLAG(0u); PG8_WAIT_L(0); PG8_BAR; PG8_MMA(1, 0, At, B0); PG8_MMA(1, 1, At, B1); PG8_BAR; PG8_SCHED;
;             PG8_LDB(B0, 1, 0); PG8_LDB(B1, 1, 1); PG8_SCHED; PG8_LDA(At, 1, 0); PG8_STAGE(PG8_SA(0, 1), a2 + hstepA, voffA);
;             PG8_WAIT_V(8); PG8_WAIT_L(0); PG8_BAR; PG8_MMA(0, 0, At, B0); PG8_MMA(0, 1, At, B1); PG8_BAR; PG8_SCHED;
;             PG8_LDA(At, 1, 1); PG8_STAGE(PG8_SB(1, 0), b3, voffB); PG8_STAGE(PG8_SB(1, 1), b3 + hstepB, voffB); PG8_STAGE(PG8_SA(1, 0), a3, voffA);
;             PG8_WAIT_V(8); PG8_WAIT_L(0); PG8_BAR; PG8_MMA(1, 0, At, B0); PG8_MMA(1, 1, At, B1); PG8_BAR; PG8_SCHED;
.Lre27:
	s_waitcnt lgkmcnt(0)
	s_barrier
	s_setprio 1
	s_waitcnt lgkmcnt(0)
	v_mfma_f32_16x16x32_bf16 v[54:57], v[122:125], v[162:165], v[54:57]
	v_mfma_f32_16x16x32_bf16 v[50:53], v[134:137], v[162:165], v[50:53]
	v_mfma_f32_16x16x32_bf16 v[38:41], v[122:125], v[190:193], v[38:41]
	v_mfma_f32_16x16x32_bf16 v[34:37], v[134:137], v[190:193], v[34:37]
	v_mfma_f32_16x16x32_bf16 v[30:33], v[122:125], v[206:209], v[30:33]
	v_mfma_f32_16x16x32_bf16 v[22:25], v[134:137], v[206:209], v[22:25]
	v_mfma_f32_16x16x32_bf16 v[14:17], v[122:125], v[214:217], v[14:17]
	v_mfma_f32_16x16x32_bf16 v[10:13], v[134:137], v[214:217], v[10:13]
	v_mfma_f32_16x16x32_bf16 v[54:57], v[126:129], v[166:169], v[54:57]
	v_mfma_f32_16x16x32_bf16 v[50:53], v[138:141], v[166:169], v[50:53]
	v_mfma_f32_16x16x32_bf16 v[38:41], v[126:129], v[202:205], v[38:41]
	v_mfma_f32_16x16x32_bf16 v[34:37], v[138:141], v[202:205], v[34:37]
	v_mfma_f32_16x16x32_bf16 v[30:33], v[126:129], v[210:213], v[30:33]
	v_mfma_f32_16x16x32_bf16 v[22:25], v[138:141], v[210:213], v[22:25]
	v_mfma_f32_16x16x32_bf16 v[14:17], v[126:129], v[218:221], v[14:17]
	v_mfma_f32_16x16x32_bf16 v[10:13], v[138:141], v[218:221], v[10:13]
	s_setprio 0
	s_setprio 1
	v_mfma_f32_16x16x32_bf16 v[62:65], v[142:145], v[162:165], v[62:65]
	v_mfma_f32_16x16x32_bf16 v[58:61], v[150:153], v[162:165], v[58:61]
	v_mfma_f32_16x16x32_bf16 v[46:49], v[142:145], v[190:193], v[46:49]
	v_mfma_f32_16x16x32_bf16 v[42:45], v[150:153], v[190:193], v[42:45]
	v_mfma_f32_16x16x32_bf16 v[26:29], v[142:145], v[206:209], v[26:29]
	v_mfma_f32_16x16x32_bf16 v[18:21], v[150:153], v[206:209], v[18:21]
	v_mfma_f32_16x16x32_bf16 v[6:9], v[142:145], v[214:217], v[6:9]
	v_mfma_f32_16x16x32_bf16 v[2:5], v[150:153], v[214:217], v[2:5]
	v_mfma_f32_16x16x32_bf16 v[62:65], v[146:149], v[166:169], v[62:65]
	v_mfma_f32_16x16x32_bf16 v[58:61], v[154:157], v[166:169], v[58:61]
	v_mfma_f32_16x16x32_bf16 v[46:49], v[146:149], v[202:205], v[46:49]
	v_mfma_f32_16x16x32_bf16 v[42:45], v[154:157], v[202:205], v[42:45]
	v_mfma_f32_16x16x32_bf16 v[26:29], v[146:149], v[210:213], v[26:29]
	v_mfma_f32_16x16x32_bf16 v[18:21], v[154:157], v[210:213], v[18:21]
	v_mfma_f32_16x16x32_bf16 v[6:9], v[146:149], v[218:221], v[6:9]
	v_mfma_f32_16x16x32_bf16 v[2:5], v[154:157], v[218:221], v[2:5]
	s_setprio 0
	s_barrier
	s_add_i32 s70, 0, 0x18000
	s_add_i32 s71, 0, 0x1c000
	v_add_u32_e32 v138, s70, v196
	v_add_u32_e32 v154, s71, v196
	ds_read_b128 v[122:125], v138
	ds_read_b128 v[126:129], v138 offset:1024
	ds_read_b128 v[134:137], v138 offset:2048
	ds_read_b128 v[138:141], v138 offset:3072
	ds_read_b128 v[142:145], v154
	ds_read_b128 v[146:149], v154 offset:1024
	ds_read_b128 v[150:153], v154 offset:2048
	ds_read_b128 v[154:157], v154 offset:3072
	s_add_u32 s0, s48, 0x2000
	s_addc_u32 s1, s49, 0
	s_mov_b32 m0, s51
	v_lshl_add_u64 v[228:229], s[0:1], 0, v[178:179]
	ds_read_b128 v[162:165], v199 offset:32768
	ds_read_b128 v[166:169], v199 offset:33792
	ds_read_b128 v[190:193], v199 offset:34816
	ds_read_b128 v[202:205], v199 offset:35840
	ds_read_b128 v[206:209], v199 offset:36864
	ds_read_b128 v[210:213], v199 offset:37888
	ds_read_b128 v[214:217], v199 offset:38912
	ds_read_b128 v[218:221], v199 offset:39936
	global_load_lds_dwordx4 v[228:229], off
	v_lshl_add_u64 v[228:229], s[0:1], 0, v[174:175]
	s_mov_b32 m0, s52
	s_nop 0
	global_load_lds_dwordx4 v[228:229], off
	s_waitcnt vmcnt(8)
	s_waitcnt lgkmcnt(0)
	s_barrier
	s_setprio 1
	s_waitcnt lgkmcnt(0)
	v_mfma_f32_16x16x32_bf16 v[118:121], v[122:125], v[162:165], v[118:121]
	v_mfma_f32_16x16x32_bf16 v[114:117], v[134:137], v[162:165], v[114:117]
	v_mfma_f32_16x16x32_bf16 v[102:105], v[122:125], v[190:193], v[102:105]
	v_mfma_f32_16x16x32_bf16 v[98:101], v[134:137], v[190:193], v[98:101]
	v_mfma_f32_16x16x32_bf16 v[86:89], v[122:125], v[206:209], v[86:89]
	v_mfma_f32_16x16x32_bf16 v[82:85], v[134:137], v[206:209], v[82:85]
	v_mfma_f32_16x16x32_bf16 v[70:73], v[122:125], v[214:217], v[70:73]
	v_mfma_f32_16x16x32_bf16 v[66:69], v[134:137], v[214:217], v[66:69]
	v_mfma_f32_16x16x32_bf16 v[118:121], v[126:129], v[166:169], v[118:121]
	v_mfma_f32_16x16x32_bf16 v[114:117], v[138:141], v[166:169], v[114:117]
	v_mfma_f32_16x16x32_bf16 v[102:105], v[126:129], v[202:205], v[102:105]
	v_mfma_f32_16x16x32_bf16 v[98:101], v[138:141], v[202:205], v[98:101]
	v_mfma_f32_16x16x32_bf16 v[86:89], v[126:129], v[210:213], v[86:89]
	v_mfma_f32_16x16x32_bf16 v[82:85], v[138:141], v[210:213], v[82:85]
	v_mfma_f32_16x16x32_bf16 v[70:73], v[126:129], v[218:221], v[70:73]
	v_mfma_f32_16x16x32_bf16 v[66:69], v[138:141], v[218:221], v[66:69]
	s_setprio 0
	s_setprio 1
	v_mfma_f32_16x16x32_bf16 v[158:161], v[142:145], v[162:165], v[158:161]
	v_mfma_f32_16x16x32_bf16 v[130:133], v[150:153], v[162:165], v[130:133]
	v_mfma_f32_16x16x32_bf16 v[110:113], v[142:145], v[190:193], v[110:113]
	v_mfma_f32_16x16x32_bf16 v[106:109], v[150:153], v[190:193], v[106:109]
	v_mfma_f32_16x16x32_bf16 v[94:97], v[142:145], v[206:209], v[94:97]
	v_mfma_f32_16x16x32_bf16 v[90:93], v[150:153], v[206:209], v[90:93]
	v_mfma_f32_16x16x32_bf16 v[78:81], v[142:145], v[214:217], v[78:81]
	v_mfma_f32_16x16x32_bf16 v[74:77], v[150:153], v[214:217], v[74:77]
	v_mfma_f32_16x16x32_bf16 v[158:161], v[146:149], v[166:169], v[158:161]
	v_mfma_f32_16x16x32_bf16 v[130:133], v[154:157], v[166:169], v[130:133]
	v_mfma_f32_16x16x32_bf16 v[110:113], v[146:149], v[202:205], v[110:113]
	v_mfma_f32_16x16x32_bf16 v[106:109], v[154:157], v[202:205], v[106:109]
	v_mfma_f32_16x16x32_bf16 v[94:97], v[146:149], v[210:213], v[94:97]
	v_mfma_f32_16x16x32_bf16 v[90:93], v[154:157], v[210:213], v[90:93]
	v_mfma_f32_16x16x32_bf16 v[78:81], v[146:149], v[218:221], v[78:81]
	v_mfma_f32_16x16x32_bf16 v[74:77], v[154:157], v[218:221], v[74:77]
	s_setprio 0
	s_barrier
; #define PG8_STAGE(bufoff, gbase, voff) do { _Pragma("unroll") for (int _i = 0; _i < 2; ++_i) \
;         __builtin_amdgcn_global_load_lds((const unsigned*)((const char*)(gbase) + (voff)[_i]), (LAS unsigned*)(lds + (bufoff) + ldsw + _i * 8192), 16, 0, 0); } while (0)
; #define PG8_LDA(dst, b, h) do { _Pragma("unroll") for (int m = 0; m < 4; ++m) _Pragma("unroll") for (int k = 0; k < 2; ++k) dst[m][k] = *(const LAS bf16x8*)(lds + PG8_SA(b, h) + aoff + m * 2048 + k * 1024); } while (0)
; #define PG8_MMA(ai, bj, At, Bt) do { __builtin_amdgcn_s_setprio(1); _Pragma("unroll") for (int m = 0; m < 4; ++m) _Pragma("unroll") for (int n = 0; n < 2; ++n) _Pragma("unroll") for (int k = 0; k < 2; ++k) \
;         acc[ai][bj][m][n] = __builtin_amdgcn_mfma_f32_16x16x32_bf16(Bt[n][k], At[m][k], acc[ai][bj][m][n], 0, 0, 0); __builtin_amdgcn_s_setprio(0); } while (0)
; #define PG8_WAIT_V(n) asm volatile("s_waitcnt vmcnt(" #n ")" ::: "memory")
; #define PG8_WAIT_L(n) asm volatile("s_waitcnt lgkmcnt(" #n ")" ::: "memory")
; #define PG8_BAR __builtin_amdgcn_s_barrier()
; #define PG8_SCHED __builtin_amdgcn_sched_barrier(0)
; template <class Epi, class Sched, bool APERM, bool ABLK = false, bool RELAX = true>
; __device__ __forceinline__ void gemm_phase(LAS unsigned char* lds, const Gemm g, const Sched& S, const Epi& E) {
;     ...
;             PG8_LDA(At, 1, 1); PG8_STAGE(PG8_SB(1, 0), b3, voffB); PG8_STAGE(PG8_SB(1, 1), b3 + hstepB, voffB); PG8_STAGE(PG8_SA(1, 0), a3, voffA);
;             PG8_WAIT_V(8); PG8_WAIT_L(0); PG8_BAR; PG8_MMA(1, 0, At, B0); PG8_MMA(1, 1, At, B1); PG8_BAR; PG8_SCHED;
;         }
;         if (wr == 0) PG8_BAR;
	s_add_i32 s0, s70, s34
	v_lshl_add_u64 v[194:195], v[194:195], 0, s[8:9]
	s_mov_b32 m0, s0
	ds_read_b128 v[162:165], v199 offset:49152
	ds_read_b128 v[166:169], v199 offset:50176
	ds_read_b128 v[190:193], v199 offset:51200
	ds_read_b128 v[202:205], v199 offset:52224
	ds_read_b128 v[206:209], v199 offset:53248
	ds_read_b128 v[210:213], v199 offset:54272
	ds_read_b128 v[214:217], v199 offset:55296
	ds_read_b128 v[218:221], v199 offset:56320
	global_load_lds_dwordx4 v[194:195], off
	s_add_i32 m0, s0, 0x2000
	s_add_u32 s0, s46, 0x40080
	v_lshl_add_u64 v[194:195], v[222:223], 0, s[8:9]
	s_addc_u32 s1, s47, 0
	s_add_i32 s46, s71, s34
	global_load_lds_dwordx4 v[194:195], off
	v_lshl_add_u64 v[194:195], s[0:1], 0, v[176:177]
	s_mov_b32 m0, s46
	s_nop 0
	global_load_lds_dwordx4 v[194:195], off
	v_lshl_add_u64 v[194:195], s[0:1], 0, v[172:173]
	s_add_i32 m0, s46, 0x2000
	s_nop 0
	global_load_lds_dwordx4 v[194:195], off
	v_lshl_add_u64 v[194:195], v[224:225], 0, s[8:9]
	s_mov_b32 m0, s55
	s_nop 0
	global_load_lds_dwordx4 v[194:195], off
	v_lshl_add_u64 v[194:195], v[226:227], 0, s[8:9]
	s_mov_b32 m0, s56
	s_nop 0
	global_load_lds_dwordx4 v[194:195], off
	s_waitcnt vmcnt(8)
	s_waitcnt lgkmcnt(0)
	s_barrier
	s_setprio 1
	s_waitcnt lgkmcnt(0)
	v_mfma_f32_16x16x32_bf16 v[54:57], v[122:125], v[162:165], v[54:57]
	v_mfma_f32_16x16x32_bf16 v[50:53], v[134:137], v[162:165], v[50:53]
	v_mfma_f32_16x16x32_bf16 v[38:41], v[122:125], v[190:193], v[38:41]
	v_mfma_f32_16x16x32_bf16 v[34:37], v[134:137], v[190:193], v[34:37]
	v_mfma_f32_16x16x32_bf16 v[30:33], v[122:125], v[206:209], v[30:33]
	v_mfma_f32_16x16x32_bf16 v[22:25], v[134:137], v[206:209], v[22:25]
	v_mfma_f32_16x16x32_bf16 v[14:17], v[122:125], v[214:217], v[14:17]
	v_mfma_f32_16x16x32_bf16 v[10:13], v[134:137], v[214:217], v[10:13]
	v_mfma_f32_16x16x32_bf16 v[54:57], v[126:129], v[166:169], v[54:57]
	v_mfma_f32_16x16x32_bf16 v[50:53], v[138:141], v[166:169], v[50:53]
	v_mfma_f32_16x16x32_bf16 v[38:41], v[126:129], v[202:205], v[38:41]
	v_mfma_f32_16x16x32_bf16 v[34:37], v[138:141], v[202:205], v[34:37]
	v_mfma_f32_16x16x32_bf16 v[30:33], v[126:129], v[210:213], v[30:33]
	v_mfma_f32_16x16x32_bf16 v[22:25], v[138:141], v[210:213], v[22:25]
	v_mfma_f32_16x16x32_bf16 v[14:17], v[126:129], v[218:221], v[14:17]
	v_mfma_f32_16x16x32_bf16 v[10:13], v[138:141], v[218:221], v[10:13]
	s_setprio 0
	s_setprio 1
	v_mfma_f32_16x16x32_bf16 v[62:65], v[142:145], v[162:165], v[62:65]
	v_mfma_f32_16x16x32_bf16 v[58:61], v[150:153], v[162:165], v[58:61]
	v_mfma_f32_16x16x32_bf16 v[46:49], v[142:145], v[190:193], v[46:49]
	v_mfma_f32_16x16x32_bf16 v[42:45], v[150:153], v[190:193], v[42:45]
	v_mfma_f32_16x16x32_bf16 v[26:29], v[142:145], v[206:209], v[26:29]
	v_mfma_f32_16x16x32_bf16 v[18:21], v[150:153], v[206:209], v[18:21]
	v_mfma_f32_16x16x32_bf16 v[6:9], v[142:145], v[214:217], v[6:9]
	v_mfma_f32_16x16x32_bf16 v[2:5], v[150:153], v[214:217], v[2:5]
	v_mfma_f32_16x16x32_bf16 v[62:65], v[146:149], v[166:169], v[62:65]
	v_mfma_f32_16x16x32_bf16 v[58:61], v[154:157], v[166:169], v[58:61]
	v_mfma_f32_16x16x32_bf16 v[46:49], v[146:149], v[202:205], v[46:49]
	v_mfma_f32_16x16x32_bf16 v[42:45], v[154:157], v[202:205], v[42:45]
	v_mfma_f32_16x16x32_bf16 v[26:29], v[146:149], v[210:213], v[26:29]
	v_mfma_f32_16x16x32_bf16 v[18:21], v[154:157], v[210:213], v[18:21]
	v_mfma_f32_16x16x32_bf16 v[6:9], v[146:149], v[218:221], v[6:9]
	v_mfma_f32_16x16x32_bf16 v[2:5], v[154:157], v[218:221], v[2:5]
	s_setprio 0
	s_barrier
	s_add_u32 s67, s67, 0x100
	s_addc_u32 s68, s68, 0
	s_cmp_gt_u32 s69, 13
	s_mov_b64 s[0:1], s[42:43]
	s_mov_b32 s46, s69
	s_cbranch_scc0 .LBB0_2173
	v_mov_b32_e32 v252, 0xbdd2d3e7
	s_and_b64 vcc, exec, s[10:11]
	s_cbranch_vccz .LBB0_2176
	s_barrier

;     __device__ __forceinline__ void operator()(const f32x4 (&acc)[2][2][4][2], const pg8::Unit& u, int wr, int wc, int fr, int fq, int buf) const {
;     ...
;             bf16_t* HH = (bf16_t*)(ws + R_HH); float* EP = (float*)(ws + WS_EDGE); float* EG = EP + EDGE_ARR / 4; float* EA = EG + EDGE_ARR / 4;
;             const int jc = u.pn * 128 + wc * 32 + 8 * fq;
;             float w0[8], w1[8], w2[8], cbv[8], pvv[8], nxx[8]; const LAS float* cl = scr + buf * 512 + wc * 32 + 8 * fq;
; #pragma unroll
;             for (int c = 0; c < 8; ++c) { w0[c] = cl[c]; w1[c] = cl[128 + c]; w2[c] = cl[256 + c]; cbv[c] = cl[384 + c];
;                 const float pv_ = __shfl_up(acc[1][0][3][c >> 2][c & 3], 1, 16), nx_ = __shfl_down(acc[0][0][0][c >> 2][c & 3], 1, 16);
;                 pvv[c] = fr == 0 ? 0.f : pv_; nxx[c] = fr == 15 ? 0.f : nx_; }
;             const size_t tok0 = (size_t)u.pm * 256 + wr * 128 + 8 * fr; const int blk = 2 * u.pm + wr;
; #pragma unroll
;             for (int ai = 0; ai < 2; ++ai)
; #pragma unroll
;                 for (int m = 0; m < 4; ++m) {
;                     const int idx = 4 * ai + m; float hv[8], av[8], gv[8];
; #pragma unroll
;                     for (int c = 0; c < 8; ++c) { const int n = c >> 2, jj = c & 3;
;                         const float cur = acc[ai][0][m][n][jj];
;                         const float prev = idx == 0 ? pvv[c] : (m > 0 ? acc[ai][0][m - 1][n][jj] : acc[0][0][3][n][jj]);
;                         const float next = idx == 7 ? nxx[c] : (m < 3 ? acc[ai][0][m + 1][n][jj] : acc[1][0][0][n][jj]);
;                         const float cv = cbv[c] + w0[c] * prev + w1[c] * cur + w2[c] * next;
;                         av[c] = cur; gv[c] = acc[ai][1][m][n][jj]; hv[c] = cv; }
;                     const bool edge0 = (idx == 0 && fr == 0), edge1 = (idx == 7 && fr == 15);
;                     if (edge0 || edge1) { const size_t eo = ((size_t)blk * 2 + (edge1 ? 1 : 0)) * FFH + jc;
; #pragma unroll
;                         for (int c = 0; c < 8; ++c) { EP[eo + c] = hv[c]; EG[eo + c] = gv[c]; EA[eo + c] = av[c]; }
;                     } else { f32x4 o0, o1;
; #pragma unroll
;                         for (int c = 0; c < 4; ++c) { o0[c] = gelu_t(hv[c]) * gv[c]; o1[c] = gelu_t(hv[4 + c]) * gv[4 + c]; }
;                         store8(HH + ((size_t)(u.pn * 4 + wc) * TT + tok0 + idx) * 32 + 8 * fq, o0, o1); }
.LBB0_2178:
	s_lshl_b32 s4, s41, 11
	v_mov_b32_e32 v202, v1
	v_mov_b32_e32 v122, v171
	s_and_b32 s4, s4, 0x800
	s_add_i32 s4, s60, s4
	v_lshlrev_b32_e32 v194, 3, v122
	v_lshl_add_u32 v150, v122, 5, s4
	v_add_u32_e32 v122, -1, v200
	v_and_b32_e32 v123, 0x70, v200
	v_cmp_lt_i32_e32 vcc, v122, v123
	s_ashr_i32 s41, s40, 31
	s_lshl_b64 s[4:5], s[40:41], 8
	v_cndmask_b32_e32 v122, v122, v200, vcc
	v_lshlrev_b32_e32 v162, 2, v122
	v_and_b32_e32 v122, 15, v200
	s_add_u32 s4, s4, s57
	v_cmp_ne_u32_e32 vcc, 15, v122
	ds_bpermute_b32 v164, v162, v14
	ds_bpermute_b32 v165, v162, v15
	s_addc_u32 s5, s5, s58
	s_lshl_b32 s21, s64, 2
	v_addc_co_u32_e32 v122, vcc, 0, v200, vcc
	s_or_b32 s21, s21, s53
	v_lshlrev_b32_e32 v163, 2, v122
	ds_read_b128 v[126:129], v150
	ds_read_b128 v[122:125], v150 offset:16
	ds_read_b128 v[138:141], v150 offset:512
	ds_read_b128 v[134:137], v150 offset:528
	ds_read_b128 v[146:149], v150 offset:1024
	ds_read_b128 v[142:145], v150 offset:1040
	ds_read_b128 v[154:157], v150 offset:1536
	ds_read_b128 v[150:153], v150 offset:1552
	s_mul_hi_i32 s23, s21, 0x9000
	s_mul_i32 s21, s21, 0x9000
	ds_bpermute_b32 v168, v162, v16
	ds_bpermute_b32 v169, v162, v17
	s_add_u32 s42, s4, s21
	s_addc_u32 s43, s5, s23
	v_cmp_eq_u32_e64 s[4:5], 0, v202
	ds_bpermute_b32 v205, v163, v118
	ds_bpermute_b32 v207, v163, v119
	ds_bpermute_b32 v209, v163, v120
	ds_bpermute_b32 v210, v163, v121
	ds_bpermute_b32 v192, v162, v10
	ds_bpermute_b32 v203, v163, v114
	ds_bpermute_b32 v193, v162, v11
	ds_bpermute_b32 v204, v163, v115
	ds_bpermute_b32 v211, v162, v12
	ds_bpermute_b32 v206, v163, v116
	ds_bpermute_b32 v212, v162, v13
	ds_bpermute_b32 v208, v163, v117
	s_waitcnt lgkmcnt(0)
	v_cndmask_b32_e64 v163, v165, 0, s[4:5]
	v_cndmask_b32_e64 v162, v164, 0, s[4:5]
	v_pk_fma_f32 v[162:163], v[126:127], v[162:163], v[154:155]
	v_cndmask_b32_e64 v165, v212, 0, s[4:5]
	v_pk_fma_f32 v[162:163], v[118:119], v[138:139], v[162:163]
	v_cndmask_b32_e64 v164, v211, 0, s[4:5]
	v_pk_fma_f32 v[166:167], v[102:103], v[146:147], v[162:163]
	v_cndmask_b32_e64 v163, v169, 0, s[4:5]
	v_cndmask_b32_e64 v162, v168, 0, s[4:5]
	v_pk_fma_f32 v[162:163], v[128:129], v[162:163], v[156:157]
	v_pk_fma_f32 v[164:165], v[124:125], v[164:165], v[152:153]
	v_pk_fma_f32 v[162:163], v[120:121], v[140:141], v[162:163]
	v_ashrrev_i32_e32 v195, 31, v194
	v_pk_fma_f32 v[168:169], v[104:105], v[148:149], v[162:163]
	v_cndmask_b32_e64 v163, v193, 0, s[4:5]
	v_cndmask_b32_e64 v162, v192, 0, s[4:5]
	v_pk_fma_f32 v[162:163], v[122:123], v[162:163], v[150:151]
	v_pk_fma_f32 v[164:165], v[116:117], v[136:137], v[164:165]
	v_pk_fma_f32 v[162:163], v[114:115], v[134:135], v[162:163]
	v_cmp_ne_u32_e32 vcc, 0, v202
	v_lshl_add_u64 v[190:191], v[194:195], 1, s[16:17]
	v_pk_fma_f32 v[162:163], v[98:99], v[142:143], v[162:163]
	v_pk_fma_f32 v[164:165], v[100:101], v[144:145], v[164:165]
	s_and_saveexec_b64 s[4:5], vcc
	s_xor_b64 s[4:5], exec, s[4:5]
	s_cbranch_execz .LBB0_2180
	v_mul_f32_e32 v195, v166, v166
	v_fmaak_f32 v195, v252, v195, 0xc0135761
	v_mul_f32_e32 v211, v162, v162
	v_mul_f32_e32 v212, v167, v167
	v_mul_f32_e32 v195, v166, v195
	v_fmaak_f32 v211, v252, v211, 0xc0135761
	v_fmaak_f32 v212, v252, v212, 0xc0135761
	v_mul_f32_e32 v211, v162, v211
	v_mul_f32_e32 v212, v167, v212
	v_exp_f32_e32 v195, v195
	v_exp_f32_e32 v211, v211
	v_exp_f32_e32 v213, v212
	v_add_f32_e32 v195, 1.0, v195
	v_rcp_f32_e32 v212, v195
	v_add_f32_e32 v195, 1.0, v211
	v_add_f32_e32 v211, 1.0, v213
	v_rcp_f32_e32 v213, v211
	v_mul_f32_e32 v211, v163, v163
	v_fmaak_f32 v211, v252, v211, 0xc0135761
	v_mul_f32_e32 v211, v163, v211
	v_exp_f32_e32 v211, v211
	v_rcp_f32_e32 v214, v195
	v_pk_mul_f32 v[166:167], v[166:167], v[212:213]
	v_mul_f32_e32 v213, v165, v165
	v_add_f32_e32 v195, 1.0, v211
	v_rcp_f32_e32 v215, v195
	v_mul_f32_e32 v195, v168, v168
	v_fmaak_f32 v195, v252, v195, 0xc0135761
	v_mul_f32_e32 v211, v164, v164
	v_mul_f32_e32 v195, v168, v195
	v_fmaak_f32 v211, v252, v211, 0xc0135761
	v_mul_f32_e32 v211, v164, v211
	v_exp_f32_e32 v195, v195
	v_exp_f32_e32 v211, v211
	v_fmaak_f32 v213, v252, v213, 0xc0135761
	v_add_f32_e32 v195, 1.0, v195
	v_rcp_f32_e32 v212, v195
	v_add_f32_e32 v195, 1.0, v211
	v_mul_f32_e32 v211, v169, v169
	v_fmaak_f32 v211, v252, v211, 0xc0135761
	v_mul_f32_e32 v211, v169, v211
	v_mul_f32_e32 v213, v165, v213
	v_exp_f32_e32 v211, v211
	v_pk_mul_f32 v[162:163], v[162:163], v[214:215]
	v_exp_f32_e32 v215, v213
	v_rcp_f32_e32 v214, v195
	v_add_f32_e32 v195, 1.0, v211
	v_rcp_f32_e32 v213, v195
	v_add_f32_e32 v195, 1.0, v215
	v_rcp_f32_e32 v215, v195
	v_lshlrev_b32_e32 v192, 3, v202
	v_ashrrev_i32_e32 v193, 31, v192
	v_pk_mul_f32 v[216:217], v[130:131], v[162:163]
	v_pk_mul_f32 v[162:163], v[168:169], v[212:213]
	v_lshl_add_u64 v[192:193], s[42:43], 0, v[192:193]
	v_pk_mul_f32 v[168:169], v[160:161], v[162:163]
	v_pk_mul_f32 v[162:163], v[164:165], v[214:215]
	v_pk_mul_f32 v[166:167], v[158:159], v[166:167]
	v_pk_mul_f32 v[212:213], v[132:133], v[162:163]
	v_lshlrev_b64 v[192:193], 6, v[192:193]
	v_lshl_add_u64 v[214:215], v[190:191], 0, v[192:193]
	v_cvt_pk_bf16_f32 v162, v166, v167
	v_cvt_pk_bf16_f32 v163, v168, v169
	v_cvt_pk_bf16_f32 v164, v216, v217
	v_cvt_pk_bf16_f32 v165, v212, v213
	global_store_dwordx4 v[214:215], v[162:165], off

; __device__ __forceinline__ void store8(bf16_t* p, const f32x4& a, const f32x4& b) { u32x4 w; w.x = pk2(a[0], a[1]); w.y = pk2(a[2], a[3]); w.z = pk2(b[0], b[1]); w.w = pk2(b[2], b[3]); *(u32x4*)p = w; }
;     __device__ __forceinline__ bool next(int i, pg8::Unit& u) const { if (!so.next(i, u)) return false; u.pm = (u.pm >> 3) * 9 + 1 + (u.pm & 7); return true; }
; __device__ __forceinline__ float gelu_t(float x) { const float u = x + 0.044715f * x * x * x; return x * __builtin_amdgcn_rcpf(1.f + __builtin_amdgcn_exp2f(-2.302208198f * u)); }
;     __device__ __forceinline__ void operator()(const f32x4 (&acc)[2][2][4][2], const pg8::Unit& u, int wr, int wc, int fr, int fq, int buf) const {
;     ...
;             for (int ai = 0; ai < 2; ++ai)
; #pragma unroll
;                 for (int m = 0; m < 4; ++m) {
;                     const int idx = 4 * ai + m; float hv[8], av[8], gv[8];
; #pragma unroll
;                     for (int c = 0; c < 8; ++c) { const int n = c >> 2, jj = c & 3;
;                         const float cur = acc[ai][0][m][n][jj];
;                         const float prev = idx == 0 ? pvv[c] : (m > 0 ? acc[ai][0][m - 1][n][jj] : acc[0][0][3][n][jj]);
;                         const float next = idx == 7 ? nxx[c] : (m < 3 ? acc[ai][0][m + 1][n][jj] : acc[1][0][0][n][jj]);
;                         const float cv = cbv[c] + w0[c] * prev + w1[c] * cur + w2[c] * next;
;                         av[c] = cur; gv[c] = acc[ai][1][m][n][jj]; hv[c] = cv; }
;                     const bool edge0 = (idx == 0 && fr == 0), edge1 = (idx == 7 && fr == 15);
;                     if (edge0 || edge1) { const size_t eo = ((size_t)blk * 2 + (edge1 ? 1 : 0)) * FFH + jc;
; #pragma unroll
;                         for (int c = 0; c < 8; ++c) { EP[eo + c] = hv[c]; EG[eo + c] = gv[c]; EA[eo + c] = av[c]; }
;                     } else { f32x4 o0, o1;
; #pragma unroll
;                         for (int c = 0; c < 4; ++c) { o0[c] = gelu_t(hv[c]) * gv[c]; o1[c] = gelu_t(hv[4 + c]) * gv[4 + c]; }
;                         store8(HH + ((size_t)(u.pn * 4 + wc) * TT + tok0 + idx) * 32 + 8 * fq, o0, o1); }
.LBB0_2182:
	s_or_b64 exec, exec, s[4:5]
	v_pk_fma_f32 v[118:119], v[118:119], v[126:127], v[154:155]
	v_pk_fma_f32 v[114:115], v[114:115], v[122:123], v[150:151]
	v_pk_fma_f32 v[118:119], v[102:103], v[138:139], v[118:119]
	v_pk_fma_f32 v[114:115], v[98:99], v[134:135], v[114:115]
	v_pk_fma_f32 v[160:161], v[86:87], v[146:147], v[118:119]
	v_pk_fma_f32 v[114:115], v[82:83], v[142:143], v[114:115]
	v_mul_f32_e32 v118, v160, v160
	v_fmaak_f32 v118, v252, v118, 0xc0135761
	v_mul_f32_e32 v119, v161, v161
	v_mul_f32_e32 v118, v160, v118
	v_fmaak_f32 v119, v252, v119, 0xc0135761
	v_mul_f32_e32 v119, v161, v119
	v_exp_f32_e32 v118, v118
	v_exp_f32_e32 v158, v119
	v_pk_fma_f32 v[120:121], v[120:121], v[128:129], v[156:157]
	v_add_f32_e32 v118, 1.0, v118
	v_rcp_f32_e32 v162, v118
	v_add_f32_e32 v118, 1.0, v158
	v_rcp_f32_e32 v163, v118
	v_pk_fma_f32 v[120:121], v[104:105], v[140:141], v[120:121]
	v_pk_fma_f32 v[116:117], v[116:117], v[124:125], v[152:153]
	v_pk_fma_f32 v[120:121], v[88:89], v[148:149], v[120:121]
	v_pk_mul_f32 v[160:161], v[160:161], v[162:163]
	v_mul_f32_e32 v162, v114, v114
	v_mul_f32_e32 v163, v115, v115
	v_fmaak_f32 v162, v252, v162, 0xc0135761
	v_fmaak_f32 v163, v252, v163, 0xc0135761
	v_mul_f32_e32 v162, v114, v162
	v_mul_f32_e32 v163, v115, v163
	v_exp_f32_e32 v162, v162
	v_exp_f32_e32 v163, v163
	v_pk_mul_f32 v[110:111], v[110:111], v[160:161]
	v_pk_fma_f32 v[116:117], v[100:101], v[136:137], v[116:117]
	v_add_f32_e32 v160, 1.0, v162
	v_add_f32_e32 v161, 1.0, v163
	v_mul_f32_e32 v162, v120, v120
	v_mul_f32_e32 v163, v121, v121
	v_fmaak_f32 v162, v252, v162, 0xc0135761
	v_fmaak_f32 v163, v252, v163, 0xc0135761
	v_mul_f32_e32 v162, v120, v162
	v_mul_f32_e32 v163, v121, v163
	v_rcp_f32_e32 v160, v160
	v_rcp_f32_e32 v161, v161
	v_exp_f32_e32 v162, v162
	v_exp_f32_e32 v163, v163
	v_pk_fma_f32 v[116:117], v[84:85], v[144:145], v[116:117]
	v_pk_mul_f32 v[114:115], v[114:115], v[160:161]
	v_add_f32_e32 v160, 1.0, v162
	v_add_f32_e32 v161, 1.0, v163
	v_mul_f32_e32 v162, v116, v116
	v_mul_f32_e32 v163, v117, v117
	v_fmaak_f32 v162, v252, v162, 0xc0135761
	v_fmaak_f32 v163, v252, v163, 0xc0135761
	v_mul_f32_e32 v162, v116, v162
	v_mul_f32_e32 v163, v117, v163
	v_exp_f32_e32 v162, v162
	v_exp_f32_e32 v163, v163
	v_rcp_f32_e32 v160, v160
	v_rcp_f32_e32 v161, v161
	v_add_f32_e32 v162, 1.0, v162
	v_add_f32_e32 v163, 1.0, v163
	v_rcp_f32_e32 v162, v162
	v_rcp_f32_e32 v163, v163
	v_pk_mul_f32 v[114:115], v[106:107], v[114:115]
	v_pk_mul_f32 v[106:107], v[120:121], v[160:161]
	v_pk_fma_f32 v[102:103], v[102:103], v[126:127], v[154:155]
	v_pk_mul_f32 v[112:113], v[112:113], v[106:107]
	v_pk_mul_f32 v[106:107], v[116:117], v[162:163]
	v_pk_fma_f32 v[102:103], v[86:87], v[138:139], v[102:103]
	v_pk_mul_f32 v[116:117], v[108:109], v[106:107]
	v_or_b32_e32 v106, 64, v192
	v_mov_b32_e32 v107, v193
	v_pk_fma_f32 v[102:103], v[70:71], v[146:147], v[102:103]
	v_lshl_add_u64 v[120:121], v[190:191], 0, v[106:107]
	v_mul_f32_e32 v107, v102, v102
	v_fmaak_f32 v107, v252, v107, 0xc0135761
	v_mul_f32_e32 v107, v102, v107
	v_exp_f32_e32 v108, v107
	v_mul_f32_e32 v107, v103, v103
	v_fmaak_f32 v107, v252, v107, 0xc0135761
	v_mul_f32_e32 v107, v103, v107
	v_exp_f32_e32 v109, v107
	v_add_f32_e32 v108, 1.0, v108
	v_pk_fma_f32 v[98:99], v[98:99], v[122:123], v[150:151]
	v_cvt_pk_bf16_f32 v106, v110, v111
	v_rcp_f32_e32 v110, v108
	v_add_f32_e32 v108, 1.0, v109
	v_pk_fma_f32 v[98:99], v[82:83], v[134:135], v[98:99]
	v_cvt_pk_bf16_f32 v107, v112, v113
	v_rcp_f32_e32 v111, v108
	v_cvt_pk_bf16_f32 v108, v114, v115
	v_cvt_pk_bf16_f32 v109, v116, v117
	v_pk_fma_f32 v[98:99], v[66:67], v[142:143], v[98:99]
	global_store_dwordx4 v[120:121], v[106:109], off
	v_pk_fma_f32 v[104:105], v[104:105], v[128:129], v[156:157]
	v_pk_mul_f32 v[102:103], v[102:103], v[110:111]
	v_mul_f32_e32 v106, v98, v98
	v_mul_f32_e32 v107, v99, v99
	v_fmaak_f32 v106, v252, v106, 0xc0135761
	v_fmaak_f32 v107, v252, v107, 0xc0135761
	v_mul_f32_e32 v106, v98, v106
	v_mul_f32_e32 v107, v99, v107
	v_exp_f32_e32 v106, v106
	v_exp_f32_e32 v107, v107
	v_pk_fma_f32 v[104:105], v[88:89], v[140:141], v[104:105]
	v_pk_mul_f32 v[94:95], v[94:95], v[102:103]
	v_pk_fma_f32 v[104:105], v[72:73], v[148:149], v[104:105]
	v_add_f32_e32 v102, 1.0, v106
	v_add_f32_e32 v103, 1.0, v107
	v_mul_f32_e32 v106, v104, v104
	v_mul_f32_e32 v107, v105, v105
	v_fmaak_f32 v106, v252, v106, 0xc0135761
	v_fmaak_f32 v107, v252, v107, 0xc0135761
	v_mul_f32_e32 v106, v104, v106
	v_mul_f32_e32 v107, v105, v107
	v_rcp_f32_e32 v102, v102
	v_rcp_f32_e32 v103, v103
	v_exp_f32_e32 v106, v106
	v_exp_f32_e32 v107, v107
	v_pk_fma_f32 v[100:101], v[100:101], v[124:125], v[152:153]
	v_pk_mul_f32 v[98:99], v[98:99], v[102:103]
	v_pk_fma_f32 v[100:101], v[84:85], v[136:137], v[100:101]
	v_add_f32_e32 v102, 1.0, v106
	v_pk_fma_f32 v[100:101], v[68:69], v[144:145], v[100:101]
	v_add_f32_e32 v103, 1.0, v107
	v_mul_f32_e32 v106, v100, v100
	v_mul_f32_e32 v107, v101, v101
	v_fmaak_f32 v106, v252, v106, 0xc0135761
	v_fmaak_f32 v107, v252, v107, 0xc0135761
	v_mul_f32_e32 v106, v100, v106
	v_mul_f32_e32 v107, v101, v107
	v_exp_f32_e32 v106, v106
	v_exp_f32_e32 v107, v107
	v_rcp_f32_e32 v102, v102
	v_rcp_f32_e32 v103, v103
	v_add_f32_e32 v106, 1.0, v106
	v_add_f32_e32 v107, 1.0, v107
	v_rcp_f32_e32 v106, v106
	v_rcp_f32_e32 v107, v107
	v_pk_mul_f32 v[98:99], v[90:91], v[98:99]
	v_pk_mul_f32 v[90:91], v[104:105], v[102:103]
	v_pk_fma_f32 v[86:87], v[86:87], v[126:127], v[154:155]
	v_pk_mul_f32 v[96:97], v[96:97], v[90:91]
	v_pk_mul_f32 v[90:91], v[100:101], v[106:107]
	v_pk_fma_f32 v[86:87], v[70:71], v[138:139], v[86:87]
	v_pk_mul_f32 v[100:101], v[92:93], v[90:91]
; __device__ __forceinline__ void store8(bf16_t* p, const f32x4& a, const f32x4& b) { u32x4 w; w.x = pk2(a[0], a[1]); w.y = pk2(a[2], a[3]); w.z = pk2(b[0], b[1]); w.w = pk2(b[2], b[3]); *(u32x4*)p = w; }
;     __device__ __forceinline__ bool next(int i, pg8::Unit& u) const { if (!so.next(i, u)) return false; u.pm = (u.pm >> 3) * 9 + 1 + (u.pm & 7); return true; }
; __device__ __forceinline__ float gelu_t(float x) { const float u = x + 0.044715f * x * x * x; return x * __builtin_amdgcn_rcpf(1.f + __builtin_amdgcn_exp2f(-2.302208198f * u)); }
;     __device__ __forceinline__ void operator()(const f32x4 (&acc)[2][2][4][2], const pg8::Unit& u, int wr, int wc, int fr, int fq, int buf) const {
;     ...
;             for (int ai = 0; ai < 2; ++ai)
; #pragma unroll
;                 for (int m = 0; m < 4; ++m) {
;                     const int idx = 4 * ai + m; float hv[8], av[8], gv[8];
; #pragma unroll
;                     for (int c = 0; c < 8; ++c) { const int n = c >> 2, jj = c & 3;
;                         const float cur = acc[ai][0][m][n][jj];
;                         const float prev = idx == 0 ? pvv[c] : (m > 0 ? acc[ai][0][m - 1][n][jj] : acc[0][0][3][n][jj]);
;                         const float next = idx == 7 ? nxx[c] : (m < 3 ? acc[ai][0][m + 1][n][jj] : acc[1][0][0][n][jj]);
;                         const float cv = cbv[c] + w0[c] * prev + w1[c] * cur + w2[c] * next;
;                         av[c] = cur; gv[c] = acc[ai][1][m][n][jj]; hv[c] = cv; }
;                     const bool edge0 = (idx == 0 && fr == 0), edge1 = (idx == 7 && fr == 15);
;                     if (edge0 || edge1) { const size_t eo = ((size_t)blk * 2 + (edge1 ? 1 : 0)) * FFH + jc;
; #pragma unroll
;                         for (int c = 0; c < 8; ++c) { EP[eo + c] = hv[c]; EG[eo + c] = gv[c]; EA[eo + c] = av[c]; }
;                     } else { f32x4 o0, o1;
; #pragma unroll
;                         for (int c = 0; c < 4; ++c) { o0[c] = gelu_t(hv[c]) * gv[c]; o1[c] = gelu_t(hv[4 + c]) * gv[4 + c]; }
;                         store8(HH + ((size_t)(u.pn * 4 + wc) * TT + tok0 + idx) * 32 + 8 * fq, o0, o1); }
	v_or_b32_e32 v90, 0x80, v192
	v_mov_b32_e32 v91, v193
	v_pk_fma_f32 v[86:87], v[54:55], v[146:147], v[86:87]
	v_lshl_add_u64 v[102:103], v[190:191], 0, v[90:91]
	v_mul_f32_e32 v91, v86, v86
	v_fmaak_f32 v91, v252, v91, 0xc0135761
	v_mul_f32_e32 v91, v86, v91
	v_exp_f32_e32 v92, v91
	v_mul_f32_e32 v91, v87, v87
	v_fmaak_f32 v91, v252, v91, 0xc0135761
	v_mul_f32_e32 v91, v87, v91
	v_exp_f32_e32 v93, v91
	v_add_f32_e32 v92, 1.0, v92
	v_pk_fma_f32 v[82:83], v[82:83], v[122:123], v[150:151]
	v_cvt_pk_bf16_f32 v90, v94, v95
	v_rcp_f32_e32 v94, v92
	v_add_f32_e32 v92, 1.0, v93
	v_pk_fma_f32 v[82:83], v[66:67], v[134:135], v[82:83]
	v_cvt_pk_bf16_f32 v91, v96, v97
	v_rcp_f32_e32 v95, v92
	v_cvt_pk_bf16_f32 v92, v98, v99
	v_cvt_pk_bf16_f32 v93, v100, v101
	v_pk_fma_f32 v[82:83], v[50:51], v[142:143], v[82:83]
	global_store_dwordx4 v[102:103], v[90:93], off
	v_pk_fma_f32 v[88:89], v[88:89], v[128:129], v[156:157]
	v_pk_mul_f32 v[86:87], v[86:87], v[94:95]
	v_mul_f32_e32 v90, v82, v82
	v_mul_f32_e32 v91, v83, v83
	v_fmaak_f32 v90, v252, v90, 0xc0135761
	v_fmaak_f32 v91, v252, v91, 0xc0135761
	v_mul_f32_e32 v90, v82, v90
	v_mul_f32_e32 v91, v83, v91
	v_exp_f32_e32 v90, v90
	v_exp_f32_e32 v91, v91
	v_pk_fma_f32 v[88:89], v[72:73], v[140:141], v[88:89]
	v_pk_mul_f32 v[78:79], v[78:79], v[86:87]
	v_pk_fma_f32 v[88:89], v[56:57], v[148:149], v[88:89]
	v_add_f32_e32 v86, 1.0, v90
	v_add_f32_e32 v87, 1.0, v91
	v_mul_f32_e32 v90, v88, v88
	v_mul_f32_e32 v91, v89, v89
	v_fmaak_f32 v90, v252, v90, 0xc0135761
	v_fmaak_f32 v91, v252, v91, 0xc0135761
	v_mul_f32_e32 v90, v88, v90
	v_mul_f32_e32 v91, v89, v91
	v_rcp_f32_e32 v86, v86
	v_rcp_f32_e32 v87, v87
	v_exp_f32_e32 v90, v90
	v_exp_f32_e32 v91, v91
	v_pk_fma_f32 v[84:85], v[84:85], v[124:125], v[152:153]
	v_pk_mul_f32 v[82:83], v[82:83], v[86:87]
	v_pk_fma_f32 v[84:85], v[68:69], v[136:137], v[84:85]
	v_add_f32_e32 v86, 1.0, v90
	v_pk_fma_f32 v[84:85], v[52:53], v[144:145], v[84:85]
	v_add_f32_e32 v87, 1.0, v91
	v_mul_f32_e32 v90, v84, v84
	v_mul_f32_e32 v91, v85, v85
	v_fmaak_f32 v90, v252, v90, 0xc0135761
	v_fmaak_f32 v91, v252, v91, 0xc0135761
	v_mul_f32_e32 v90, v84, v90
	v_mul_f32_e32 v91, v85, v91
	v_exp_f32_e32 v90, v90
	v_exp_f32_e32 v91, v91
	v_rcp_f32_e32 v86, v86
	v_rcp_f32_e32 v87, v87
	v_add_f32_e32 v90, 1.0, v90
	v_add_f32_e32 v91, 1.0, v91
	v_rcp_f32_e32 v90, v90
	v_rcp_f32_e32 v91, v91
	v_pk_mul_f32 v[82:83], v[74:75], v[82:83]
	v_pk_mul_f32 v[74:75], v[88:89], v[86:87]
	v_pk_fma_f32 v[70:71], v[70:71], v[126:127], v[154:155]
	v_pk_mul_f32 v[80:81], v[80:81], v[74:75]
	v_pk_mul_f32 v[74:75], v[84:85], v[90:91]
	v_pk_fma_f32 v[70:71], v[54:55], v[138:139], v[70:71]
	v_pk_mul_f32 v[84:85], v[76:77], v[74:75]
	v_or_b32_e32 v74, 0xc0, v192
	v_mov_b32_e32 v75, v193
	v_pk_fma_f32 v[70:71], v[38:39], v[146:147], v[70:71]
	v_lshl_add_u64 v[86:87], v[190:191], 0, v[74:75]
	v_mul_f32_e32 v75, v70, v70
	v_fmaak_f32 v75, v252, v75, 0xc0135761
	v_mul_f32_e32 v75, v70, v75
	v_exp_f32_e32 v76, v75
	v_mul_f32_e32 v75, v71, v71
	v_fmaak_f32 v75, v252, v75, 0xc0135761
	v_mul_f32_e32 v75, v71, v75
	v_exp_f32_e32 v77, v75
	v_add_f32_e32 v76, 1.0, v76
	v_pk_fma_f32 v[66:67], v[66:67], v[122:123], v[150:151]
	v_cvt_pk_bf16_f32 v74, v78, v79
	v_rcp_f32_e32 v78, v76
	v_add_f32_e32 v76, 1.0, v77
	v_pk_fma_f32 v[66:67], v[50:51], v[134:135], v[66:67]
	v_cvt_pk_bf16_f32 v75, v80, v81
	v_rcp_f32_e32 v79, v76
	v_cvt_pk_bf16_f32 v76, v82, v83
	v_cvt_pk_bf16_f32 v77, v84, v85
	v_pk_fma_f32 v[66:67], v[34:35], v[142:143], v[66:67]
	global_store_dwordx4 v[86:87], v[74:77], off
	v_pk_fma_f32 v[72:73], v[72:73], v[128:129], v[156:157]
	v_pk_mul_f32 v[70:71], v[70:71], v[78:79]
	v_mul_f32_e32 v74, v66, v66
	v_mul_f32_e32 v75, v67, v67
	v_fmaak_f32 v74, v252, v74, 0xc0135761
	v_fmaak_f32 v75, v252, v75, 0xc0135761
	v_mul_f32_e32 v74, v66, v74
	v_mul_f32_e32 v75, v67, v75
	v_exp_f32_e32 v74, v74
	v_exp_f32_e32 v75, v75
	v_pk_fma_f32 v[72:73], v[56:57], v[140:141], v[72:73]
	v_pk_mul_f32 v[62:63], v[62:63], v[70:71]
	v_pk_fma_f32 v[72:73], v[40:41], v[148:149], v[72:73]
	v_add_f32_e32 v70, 1.0, v74
	v_add_f32_e32 v71, 1.0, v75
	v_mul_f32_e32 v74, v72, v72
	v_mul_f32_e32 v75, v73, v73
	v_fmaak_f32 v74, v252, v74, 0xc0135761
	v_fmaak_f32 v75, v252, v75, 0xc0135761
	v_mul_f32_e32 v74, v72, v74
	v_mul_f32_e32 v75, v73, v75
	v_rcp_f32_e32 v70, v70
	v_rcp_f32_e32 v71, v71
	v_exp_f32_e32 v74, v74
	v_exp_f32_e32 v75, v75
	v_pk_fma_f32 v[68:69], v[68:69], v[124:125], v[152:153]
	v_pk_mul_f32 v[66:67], v[66:67], v[70:71]
	v_pk_fma_f32 v[68:69], v[52:53], v[136:137], v[68:69]
	v_add_f32_e32 v70, 1.0, v74
	v_pk_fma_f32 v[68:69], v[36:37], v[144:145], v[68:69]
	v_add_f32_e32 v71, 1.0, v75
	v_mul_f32_e32 v74, v68, v68
	v_mul_f32_e32 v75, v69, v69
	v_fmaak_f32 v74, v252, v74, 0xc0135761
	v_fmaak_f32 v75, v252, v75, 0xc0135761
	v_mul_f32_e32 v74, v68, v74
	v_mul_f32_e32 v75, v69, v75
	v_exp_f32_e32 v74, v74
	v_exp_f32_e32 v75, v75
	v_rcp_f32_e32 v70, v70
	v_rcp_f32_e32 v71, v71
	v_add_f32_e32 v74, 1.0, v74
	v_add_f32_e32 v75, 1.0, v75
	v_rcp_f32_e32 v74, v74
	v_rcp_f32_e32 v75, v75
	v_pk_mul_f32 v[66:67], v[58:59], v[66:67]
	v_pk_mul_f32 v[58:59], v[72:73], v[70:71]
	v_pk_fma_f32 v[54:55], v[54:55], v[126:127], v[154:155]
	v_pk_mul_f32 v[64:65], v[64:65], v[58:59]
	v_pk_mul_f32 v[58:59], v[68:69], v[74:75]
	v_pk_fma_f32 v[54:55], v[38:39], v[138:139], v[54:55]
	v_pk_mul_f32 v[68:69], v[60:61], v[58:59]
	v_or_b32_e32 v58, 0x100, v192
	v_mov_b32_e32 v59, v193
	v_pk_fma_f32 v[54:55], v[30:31], v[146:147], v[54:55]
	v_lshl_add_u64 v[70:71], v[190:191], 0, v[58:59]
	v_mul_f32_e32 v59, v54, v54
	v_fmaak_f32 v59, v252, v59, 0xc0135761
; __device__ __forceinline__ void store8(bf16_t* p, const f32x4& a, const f32x4& b) { u32x4 w; w.x = pk2(a[0], a[1]); w.y = pk2(a[2], a[3]); w.z = pk2(b[0], b[1]); w.w = pk2(b[2], b[3]); *(u32x4*)p = w; }
;     __device__ __forceinline__ bool next(int i, pg8::Unit& u) const { if (!so.next(i, u)) return false; u.pm = (u.pm >> 3) * 9 + 1 + (u.pm & 7); return true; }
; __device__ __forceinline__ float gelu_t(float x) { const float u = x + 0.044715f * x * x * x; return x * __builtin_amdgcn_rcpf(1.f + __builtin_amdgcn_exp2f(-2.302208198f * u)); }
;     __device__ __forceinline__ void operator()(const f32x4 (&acc)[2][2][4][2], const pg8::Unit& u, int wr, int wc, int fr, int fq, int buf) const {
;     ...
;             for (int ai = 0; ai < 2; ++ai)
; #pragma unroll
;                 for (int m = 0; m < 4; ++m) {
;                     const int idx = 4 * ai + m; float hv[8], av[8], gv[8];
; #pragma unroll
;                     for (int c = 0; c < 8; ++c) { const int n = c >> 2, jj = c & 3;
;                         const float cur = acc[ai][0][m][n][jj];
;                         const float prev = idx == 0 ? pvv[c] : (m > 0 ? acc[ai][0][m - 1][n][jj] : acc[0][0][3][n][jj]);
;                         const float next = idx == 7 ? nxx[c] : (m < 3 ? acc[ai][0][m + 1][n][jj] : acc[1][0][0][n][jj]);
;                         const float cv = cbv[c] + w0[c] * prev + w1[c] * cur + w2[c] * next;
;                         av[c] = cur; gv[c] = acc[ai][1][m][n][jj]; hv[c] = cv; }
;                     const bool edge0 = (idx == 0 && fr == 0), edge1 = (idx == 7 && fr == 15);
;                     if (edge0 || edge1) { const size_t eo = ((size_t)blk * 2 + (edge1 ? 1 : 0)) * FFH + jc;
; #pragma unroll
;                         for (int c = 0; c < 8; ++c) { EP[eo + c] = hv[c]; EG[eo + c] = gv[c]; EA[eo + c] = av[c]; }
;                     } else { f32x4 o0, o1;
; #pragma unroll
;                         for (int c = 0; c < 4; ++c) { o0[c] = gelu_t(hv[c]) * gv[c]; o1[c] = gelu_t(hv[4 + c]) * gv[4 + c]; }
;                         store8(HH + ((size_t)(u.pn * 4 + wc) * TT + tok0 + idx) * 32 + 8 * fq, o0, o1); }
	v_mul_f32_e32 v59, v54, v59
	v_exp_f32_e32 v60, v59
	v_mul_f32_e32 v59, v55, v55
	v_fmaak_f32 v59, v252, v59, 0xc0135761
	v_mul_f32_e32 v59, v55, v59
	v_exp_f32_e32 v61, v59
	v_add_f32_e32 v60, 1.0, v60
	v_pk_fma_f32 v[50:51], v[50:51], v[122:123], v[150:151]
	v_cvt_pk_bf16_f32 v58, v62, v63
	v_rcp_f32_e32 v62, v60
	v_add_f32_e32 v60, 1.0, v61
	v_pk_fma_f32 v[50:51], v[34:35], v[134:135], v[50:51]
	v_cvt_pk_bf16_f32 v59, v64, v65
	v_rcp_f32_e32 v63, v60
	v_cvt_pk_bf16_f32 v60, v66, v67
	v_cvt_pk_bf16_f32 v61, v68, v69
	v_pk_fma_f32 v[50:51], v[22:23], v[142:143], v[50:51]
	global_store_dwordx4 v[70:71], v[58:61], off
	v_pk_fma_f32 v[56:57], v[56:57], v[128:129], v[156:157]
	v_pk_mul_f32 v[54:55], v[54:55], v[62:63]
	v_mul_f32_e32 v58, v50, v50
	v_mul_f32_e32 v59, v51, v51
	v_fmaak_f32 v58, v252, v58, 0xc0135761
	v_fmaak_f32 v59, v252, v59, 0xc0135761
	v_mul_f32_e32 v58, v50, v58
	v_mul_f32_e32 v59, v51, v59
	v_exp_f32_e32 v58, v58
	v_exp_f32_e32 v59, v59
	v_pk_fma_f32 v[56:57], v[40:41], v[140:141], v[56:57]
	v_pk_mul_f32 v[46:47], v[46:47], v[54:55]
	v_pk_fma_f32 v[56:57], v[32:33], v[148:149], v[56:57]
	v_add_f32_e32 v54, 1.0, v58
	v_add_f32_e32 v55, 1.0, v59
	v_mul_f32_e32 v58, v56, v56
	v_mul_f32_e32 v59, v57, v57
	v_fmaak_f32 v58, v252, v58, 0xc0135761
	v_fmaak_f32 v59, v252, v59, 0xc0135761
	v_mul_f32_e32 v58, v56, v58
	v_mul_f32_e32 v59, v57, v59
	v_rcp_f32_e32 v54, v54
	v_rcp_f32_e32 v55, v55
	v_exp_f32_e32 v58, v58
	v_exp_f32_e32 v59, v59
	v_pk_fma_f32 v[52:53], v[52:53], v[124:125], v[152:153]
	v_pk_mul_f32 v[50:51], v[50:51], v[54:55]
	v_pk_fma_f32 v[52:53], v[36:37], v[136:137], v[52:53]
	v_add_f32_e32 v54, 1.0, v58
	v_pk_fma_f32 v[52:53], v[24:25], v[144:145], v[52:53]
	v_add_f32_e32 v55, 1.0, v59
	v_mul_f32_e32 v58, v52, v52
	v_mul_f32_e32 v59, v53, v53
	v_fmaak_f32 v58, v252, v58, 0xc0135761
	v_fmaak_f32 v59, v252, v59, 0xc0135761
	v_mul_f32_e32 v58, v52, v58
	v_mul_f32_e32 v59, v53, v59
	v_exp_f32_e32 v58, v58
	v_exp_f32_e32 v59, v59
	v_rcp_f32_e32 v54, v54
	v_rcp_f32_e32 v55, v55
	v_add_f32_e32 v58, 1.0, v58
	v_add_f32_e32 v59, 1.0, v59
	v_rcp_f32_e32 v58, v58
	v_rcp_f32_e32 v59, v59
	v_pk_mul_f32 v[50:51], v[42:43], v[50:51]
	v_pk_mul_f32 v[42:43], v[56:57], v[54:55]
	v_pk_fma_f32 v[38:39], v[38:39], v[126:127], v[154:155]
	v_pk_mul_f32 v[48:49], v[48:49], v[42:43]
	v_pk_mul_f32 v[42:43], v[52:53], v[58:59]
	v_pk_fma_f32 v[38:39], v[30:31], v[138:139], v[38:39]
	v_pk_mul_f32 v[52:53], v[44:45], v[42:43]
	v_or_b32_e32 v42, 0x140, v192
	v_mov_b32_e32 v43, v193
	v_pk_fma_f32 v[38:39], v[14:15], v[146:147], v[38:39]
	v_lshl_add_u64 v[54:55], v[190:191], 0, v[42:43]
	v_mul_f32_e32 v43, v38, v38
	v_fmaak_f32 v43, v252, v43, 0xc0135761
	v_mul_f32_e32 v43, v38, v43
	v_exp_f32_e32 v44, v43
	v_mul_f32_e32 v43, v39, v39
	v_fmaak_f32 v43, v252, v43, 0xc0135761
	v_mul_f32_e32 v43, v39, v43
	v_exp_f32_e32 v45, v43
	v_add_f32_e32 v44, 1.0, v44
	v_pk_fma_f32 v[34:35], v[34:35], v[122:123], v[150:151]
	v_cvt_pk_bf16_f32 v42, v46, v47
	v_rcp_f32_e32 v46, v44
	v_add_f32_e32 v44, 1.0, v45
	v_pk_fma_f32 v[34:35], v[22:23], v[134:135], v[34:35]
	v_cvt_pk_bf16_f32 v43, v48, v49
	v_rcp_f32_e32 v47, v44
	v_cvt_pk_bf16_f32 v44, v50, v51
	v_cvt_pk_bf16_f32 v45, v52, v53
	v_pk_fma_f32 v[34:35], v[10:11], v[142:143], v[34:35]
	global_store_dwordx4 v[54:55], v[42:45], off
	v_pk_fma_f32 v[40:41], v[40:41], v[128:129], v[156:157]
	v_pk_mul_f32 v[38:39], v[38:39], v[46:47]
	v_mul_f32_e32 v42, v34, v34
	v_mul_f32_e32 v43, v35, v35
	v_fmaak_f32 v42, v252, v42, 0xc0135761
	v_fmaak_f32 v43, v252, v43, 0xc0135761
	v_mul_f32_e32 v42, v34, v42
	v_mul_f32_e32 v43, v35, v43
	v_exp_f32_e32 v42, v42
	v_exp_f32_e32 v43, v43
	v_pk_fma_f32 v[40:41], v[32:33], v[140:141], v[40:41]
	v_pk_mul_f32 v[26:27], v[26:27], v[38:39]
	v_pk_fma_f32 v[40:41], v[16:17], v[148:149], v[40:41]
	v_add_f32_e32 v38, 1.0, v42
	v_add_f32_e32 v39, 1.0, v43
	v_mul_f32_e32 v42, v40, v40
	v_mul_f32_e32 v43, v41, v41
	v_fmaak_f32 v42, v252, v42, 0xc0135761
	v_fmaak_f32 v43, v252, v43, 0xc0135761
	v_mul_f32_e32 v42, v40, v42
	v_mul_f32_e32 v43, v41, v43
	v_rcp_f32_e32 v38, v38
	v_rcp_f32_e32 v39, v39
	v_exp_f32_e32 v42, v42
	v_exp_f32_e32 v43, v43
	v_pk_fma_f32 v[36:37], v[36:37], v[124:125], v[152:153]
	v_pk_mul_f32 v[34:35], v[34:35], v[38:39]
	v_pk_fma_f32 v[36:37], v[24:25], v[136:137], v[36:37]
	v_add_f32_e32 v38, 1.0, v42
	v_pk_fma_f32 v[36:37], v[12:13], v[144:145], v[36:37]
	v_add_f32_e32 v39, 1.0, v43
	v_mul_f32_e32 v42, v36, v36
	v_mul_f32_e32 v43, v37, v37
	v_fmaak_f32 v42, v252, v42, 0xc0135761
	v_fmaak_f32 v43, v252, v43, 0xc0135761
	v_mul_f32_e32 v42, v36, v42
	v_mul_f32_e32 v43, v37, v43
	v_exp_f32_e32 v42, v42
	v_exp_f32_e32 v43, v43
	v_rcp_f32_e32 v38, v38
	v_rcp_f32_e32 v39, v39
	v_add_f32_e32 v42, 1.0, v42
	v_add_f32_e32 v43, 1.0, v43
	v_rcp_f32_e32 v42, v42
	v_rcp_f32_e32 v43, v43
	v_pk_mul_f32 v[34:35], v[18:19], v[34:35]
	v_pk_mul_f32 v[18:19], v[40:41], v[38:39]
	v_cmp_eq_u32_e64 s[4:5], 15, v202
	v_pk_mul_f32 v[28:29], v[28:29], v[18:19]
	v_pk_mul_f32 v[18:19], v[36:37], v[42:43]
	v_cndmask_b32_e64 v131, v207, 0, s[4:5]
	v_pk_mul_f32 v[36:37], v[20:21], v[18:19]
	v_or_b32_e32 v18, 0x180, v192
	v_mov_b32_e32 v19, v193
	v_lshl_add_u64 v[38:39], v[190:191], 0, v[18:19]
	v_cvt_pk_bf16_f32 v18, v26, v27
	v_cvt_pk_bf16_f32 v19, v28, v29
	v_cvt_pk_bf16_f32 v20, v34, v35
	v_cvt_pk_bf16_f32 v21, v36, v37
	global_store_dwordx4 v[38:39], v[18:21], off
	v_cndmask_b32_e64 v130, v205, 0, s[4:5]
	v_cndmask_b32_e64 v133, v210, 0, s[4:5]
	v_pk_fma_f32 v[18:19], v[30:31], v[126:127], v[154:155]
	v_cndmask_b32_e64 v132, v209, 0, s[4:5]
	v_pk_fma_f32 v[18:19], v[14:15], v[138:139], v[18:19]
	v_pk_fma_f32 v[20:21], v[24:25], v[124:125], v[152:153]
	v_pk_fma_f32 v[26:27], v[146:147], v[130:131], v[18:19]
	v_pk_fma_f32 v[18:19], v[32:33], v[128:129], v[156:157]
	v_cndmask_b32_e64 v119, v204, 0, s[4:5]
	v_pk_fma_f32 v[18:19], v[16:17], v[140:141], v[18:19]
	v_cndmask_b32_e64 v118, v203, 0, s[4:5]
	v_pk_fma_f32 v[28:29], v[148:149], v[132:133], v[18:19]
	v_pk_fma_f32 v[18:19], v[22:23], v[122:123], v[150:151]
	v_cndmask_b32_e64 v159, v208, 0, s[4:5]
	v_cndmask_b32_e64 v158, v206, 0, s[4:5]
	v_pk_fma_f32 v[18:19], v[10:11], v[134:135], v[18:19]
	v_pk_fma_f32 v[20:21], v[12:13], v[136:137], v[20:21]
	v_cmp_ne_u32_e32 vcc, 15, v202
	v_pk_fma_f32 v[18:19], v[142:143], v[118:119], v[18:19]
	v_pk_fma_f32 v[20:21], v[144:145], v[158:159], v[20:21]
	s_and_saveexec_b64 s[4:5], vcc
	s_xor_b64 s[4:5], exec, s[4:5]
	s_cbranch_execnz .LBB0_2185
	s_andn2_saveexec_b64 s[4:5], s[4:5]
	s_cbranch_execnz .LBB0_2186

; __device__ __forceinline__ void store8(bf16_t* p, const f32x4& a, const f32x4& b) { u32x4 w; w.x = pk2(a[0], a[1]); w.y = pk2(a[2], a[3]); w.z = pk2(b[0], b[1]); w.w = pk2(b[2], b[3]); *(u32x4*)p = w; }
;     __device__ __forceinline__ bool next(int i, pg8::Unit& u) const { if (!so.next(i, u)) return false; u.pm = (u.pm >> 3) * 9 + 1 + (u.pm & 7); return true; }
; __device__ __forceinline__ float gelu_t(float x) { const float u = x + 0.044715f * x * x * x; return x * __builtin_amdgcn_rcpf(1.f + __builtin_amdgcn_exp2f(-2.302208198f * u)); }
;     __device__ __forceinline__ void operator()(const f32x4 (&acc)[2][2][4][2], const pg8::Unit& u, int wr, int wc, int fr, int fq, int buf) const {
;     ...
;             for (int ai = 0; ai < 2; ++ai)
; #pragma unroll
;                 for (int m = 0; m < 4; ++m) {
;                     const int idx = 4 * ai + m; float hv[8], av[8], gv[8];
; #pragma unroll
;                     for (int c = 0; c < 8; ++c) { const int n = c >> 2, jj = c & 3;
;                         const float cur = acc[ai][0][m][n][jj];
;                         const float prev = idx == 0 ? pvv[c] : (m > 0 ? acc[ai][0][m - 1][n][jj] : acc[0][0][3][n][jj]);
;                         const float next = idx == 7 ? nxx[c] : (m < 3 ? acc[ai][0][m + 1][n][jj] : acc[1][0][0][n][jj]);
;                         const float cv = cbv[c] + w0[c] * prev + w1[c] * cur + w2[c] * next;
;                         av[c] = cur; gv[c] = acc[ai][1][m][n][jj]; hv[c] = cv; }
;                     const bool edge0 = (idx == 0 && fr == 0), edge1 = (idx == 7 && fr == 15);
;                     if (edge0 || edge1) { const size_t eo = ((size_t)blk * 2 + (edge1 ? 1 : 0)) * FFH + jc;
; #pragma unroll
;                         for (int c = 0; c < 8; ++c) { EP[eo + c] = hv[c]; EG[eo + c] = gv[c]; EA[eo + c] = av[c]; }
;                     } else { f32x4 o0, o1;
; #pragma unroll
;                         for (int c = 0; c < 4; ++c) { o0[c] = gelu_t(hv[c]) * gv[c]; o1[c] = gelu_t(hv[4 + c]) * gv[4 + c]; }
;                         store8(HH + ((size_t)(u.pn * 4 + wc) * TT + tok0 + idx) * 32 + 8 * fq, o0, o1); }
.LBB0_2185:
	v_mul_f32_e32 v13, v18, v18
	v_mul_f32_e32 v16, v27, v27
	v_fmaak_f32 v13, v252, v13, 0xc0135761
	v_fmaak_f32 v16, v252, v16, 0xc0135761
	v_mul_f32_e32 v13, v18, v13
	v_mul_f32_e32 v16, v27, v16
	v_exp_f32_e32 v13, v13
	v_exp_f32_e32 v16, v16
	v_mul_f32_e32 v23, v20, v20
	v_fmaak_f32 v23, v252, v23, 0xc0135761
	v_add_f32_e32 v17, 1.0, v13
	v_add_f32_e32 v13, 1.0, v16
	v_mul_f32_e32 v16, v19, v19
	v_fmaak_f32 v16, v252, v16, 0xc0135761
	v_mul_f32_e32 v16, v19, v16
	v_exp_f32_e32 v22, v16
	v_rcp_f32_e32 v16, v17
	v_mul_f32_e32 v23, v20, v23
	v_add_f32_e32 v17, 1.0, v22
	v_mul_f32_e32 v22, v28, v28
	v_fmaak_f32 v22, v252, v22, 0xc0135761
	v_mul_f32_e32 v22, v28, v22
	v_rcp_f32_e32 v17, v17
	v_exp_f32_e32 v22, v22
	v_exp_f32_e32 v23, v23
	v_mul_f32_e32 v12, v26, v26
	v_pk_mul_f32 v[16:17], v[18:19], v[16:17]
	v_add_f32_e32 v18, 1.0, v22
	v_mul_f32_e32 v22, v29, v29
	v_fmaak_f32 v22, v252, v22, 0xc0135761
	v_mul_f32_e32 v22, v29, v22
	v_add_f32_e32 v19, 1.0, v23
	v_exp_f32_e32 v23, v22
	v_mul_f32_e32 v22, v21, v21
	v_fmaak_f32 v12, v252, v12, 0xc0135761
	v_fmaak_f32 v22, v252, v22, 0xc0135761
	v_mul_f32_e32 v12, v26, v12
	v_mul_f32_e32 v22, v21, v22
	v_exp_f32_e32 v12, v12
	v_exp_f32_e32 v24, v22
	v_rcp_f32_e32 v22, v19
	v_add_f32_e32 v19, 1.0, v23
	v_add_f32_e32 v12, 1.0, v12
	v_rcp_f32_e32 v18, v18
	v_rcp_f32_e32 v19, v19
	v_add_f32_e32 v23, 1.0, v24
	v_rcp_f32_e32 v12, v12
	v_rcp_f32_e32 v13, v13
	v_rcp_f32_e32 v23, v23
	v_pk_mul_f32 v[24:25], v[2:3], v[16:17]
	v_pk_mul_f32 v[16:17], v[28:29], v[18:19]
	v_pk_mul_f32 v[12:13], v[26:27], v[12:13]
	v_pk_mul_f32 v[18:19], v[8:9], v[16:17]
	v_pk_mul_f32 v[16:17], v[20:21], v[22:23]
	v_pk_mul_f32 v[12:13], v[6:7], v[12:13]
	v_pk_mul_f32 v[20:21], v[4:5], v[16:17]
	v_or_b32_e32 v192, 0x1c0, v192
	v_lshl_add_u64 v[22:23], v[190:191], 0, v[192:193]
	v_cvt_pk_bf16_f32 v16, v12, v13
	v_cvt_pk_bf16_f32 v17, v18, v19
	v_cvt_pk_bf16_f32 v18, v24, v25
	v_cvt_pk_bf16_f32 v19, v20, v21
	global_store_dwordx4 v[22:23], v[16:19], off
	s_andn2_saveexec_b64 s[4:5], s[4:5]
	s_cbranch_execz .LBB0_2184
